# stack17 + first K-loop iteration after a unit's epilogue peeled with its first two vmcnt waits relaxed to 26 (output stores need not retire before the next unit's first MFMA blocks)
# baseline (speedup 1.0000x reference)
.LBB0_323:
	s_add_i32 m0, s19, 0x18000
	v_lshl_add_u64 v[2:3], v[2:3], 0, s[94:95]
	s_waitcnt vmcnt(2)
	s_barrier
	global_load_lds_dwordx4 v[2:3], off
	v_lshl_add_u64 v[2:3], v[4:5], 0, s[94:95]
	s_add_i32 m0, s19, 0x1a000
	s_add_i32 s56, s19, 0x8000
	global_load_lds_dwordx4 v[2:3], off
	v_lshl_add_u64 v[2:3], v[10:11], 0, s[94:95]
	s_mov_b32 m0, s56
	s_add_i32 s57, s19, 0xa000
	global_load_lds_dwordx4 v[2:3], off
	v_lshl_add_u64 v[2:3], v[12:13], 0, s[94:95]
	s_mov_b32 m0, s57
	v_or_b32_e32 v142, s7, v20
	global_load_lds_dwordx4 v[2:3], off
	s_add_i32 m0, s19, 0x1c000
	v_lshl_add_u64 v[2:3], v[6:7], 0, s[94:95]
	global_load_lds_dwordx4 v[2:3], off
	v_lshl_add_u64 v[2:3], v[8:9], 0, s[94:95]
	s_add_i32 m0, s19, 0x1e000
	v_lshlrev_b32_e32 v23, 6, v142
	global_load_lds_dwordx4 v[2:3], off
	s_movk_i32 s7, 0x3c0
	v_lshlrev_b32_e32 v24, 2, v142
	v_add_u32_e32 v2, v16, v14
	s_lshr_b32 s55, s15, 6
	v_and_or_b32 v23, v23, s7, v21
	v_and_b32_e32 v24, 32, v24
	v_add_lshl_u32 v2, v2, v15, 1
	v_mov_b32_e32 v2, v246
	v_mov_b32_e32 v3, v1
	v_bitop3_b32 v23, v23, s6, v24 bitop3:0xde
	s_lshl_b32 s6, s1, 12
	v_lshlrev_b32_e32 v25, 2, v20
	s_waitcnt vmcnt(6)
	s_add_i32 s58, s55, -2
	v_lshl_add_u64 v[136:137], s[80:81], 0, v[2:3]
	v_add_u32_e32 v2, v19, v17
	v_lshlrev_b32_e32 v22, 3, v22
	v_lshl_or_b32 v24, v20, 6, v21
	v_and_b32_e32 v25, 32, v25
	s_cmpk_lt_u32 s0, 0x100
	v_lshlrev_b32_e32 v4, 4, v20
	v_add_lshl_u32 v2, v2, v18, 1
	v_mov_b32_e32 v2, v247
	v_bitop3_b32 v143, v24, s6, v25 bitop3:0xde
	v_lshl_or_b32 v144, s1, 5, v22
	v_or_b32_e32 v145, v142, v21
	s_cselect_b64 s[10:11], -1, 0
	s_mov_b32 s13, s81
	v_lshl_add_u64 v[138:139], s[80:81], 0, v[2:3]
	s_mov_b32 s59, 0
	v_add_u32_e32 v146, 0, v23
	v_lshrrev_b32_e32 v245, 10, v146
	v_lshl_or_b32 v146, v245, 10, v243
	v_add_u32_e32 v147, s18, v4
	s_barrier
	s_mov_b32 s101, 0
	s_branch .LBB0_326

.LBB0_333:
	s_add_u32 s16, s16, 0x80
	s_addc_u32 s17, s17, 0
	s_add_u32 s64, s20, 0x100
	v_mov_b32_e32 v2, 0
	s_addc_u32 s65, s21, 0
	s_mov_b32 s20, 0
	v_mov_b32_e32 v3, v2
	v_mov_b32_e32 v4, v2
	v_mov_b32_e32 v5, v2
	v_mov_b32_e32 v6, v2
	v_mov_b32_e32 v7, v2
	v_mov_b32_e32 v8, v2
	v_mov_b32_e32 v9, v2
	v_mov_b32_e32 v18, v2
	v_mov_b32_e32 v19, v2
	v_mov_b32_e32 v20, v2
	v_mov_b32_e32 v21, v2
	v_mov_b32_e32 v22, v2
	v_mov_b32_e32 v23, v2
	v_mov_b32_e32 v24, v2
	v_mov_b32_e32 v25, v2
	v_mov_b32_e32 v34, v2
	v_mov_b32_e32 v35, v2
	v_mov_b32_e32 v36, v2
	v_mov_b32_e32 v37, v2
	v_mov_b32_e32 v38, v2
	v_mov_b32_e32 v39, v2
	v_mov_b32_e32 v40, v2
	v_mov_b32_e32 v41, v2
	v_mov_b32_e32 v50, v2
	v_mov_b32_e32 v51, v2
	v_mov_b32_e32 v52, v2
	v_mov_b32_e32 v53, v2
	v_mov_b32_e32 v54, v2
	v_mov_b32_e32 v55, v2
	v_mov_b32_e32 v56, v2
	v_mov_b32_e32 v57, v2
	v_mov_b32_e32 v10, v2
	v_mov_b32_e32 v11, v2
	v_mov_b32_e32 v12, v2
	v_mov_b32_e32 v13, v2
	v_mov_b32_e32 v14, v2
	v_mov_b32_e32 v15, v2
	v_mov_b32_e32 v16, v2
	v_mov_b32_e32 v17, v2
	v_mov_b32_e32 v26, v2
	v_mov_b32_e32 v27, v2
	v_mov_b32_e32 v28, v2
	v_mov_b32_e32 v29, v2
	v_mov_b32_e32 v30, v2
	v_mov_b32_e32 v31, v2
	v_mov_b32_e32 v32, v2
	v_mov_b32_e32 v33, v2
	v_mov_b32_e32 v42, v2
	v_mov_b32_e32 v43, v2
	v_mov_b32_e32 v44, v2
	v_mov_b32_e32 v45, v2
	v_mov_b32_e32 v46, v2
	v_mov_b32_e32 v47, v2
	v_mov_b32_e32 v48, v2
	v_mov_b32_e32 v49, v2
	v_mov_b32_e32 v58, v2
	v_mov_b32_e32 v59, v2
	v_mov_b32_e32 v60, v2
	v_mov_b32_e32 v61, v2
	v_mov_b32_e32 v62, v2
	v_mov_b32_e32 v63, v2
	v_mov_b32_e32 v64, v2
	v_mov_b32_e32 v65, v2
	v_mov_b32_e32 v66, v2
	v_mov_b32_e32 v67, v2
	v_mov_b32_e32 v68, v2
	v_mov_b32_e32 v69, v2
	v_mov_b32_e32 v70, v2
	v_mov_b32_e32 v71, v2
	v_mov_b32_e32 v72, v2
	v_mov_b32_e32 v73, v2
	v_mov_b32_e32 v82, v2
	v_mov_b32_e32 v83, v2
	v_mov_b32_e32 v84, v2
	v_mov_b32_e32 v85, v2
	v_mov_b32_e32 v86, v2
	v_mov_b32_e32 v87, v2
	v_mov_b32_e32 v88, v2
	v_mov_b32_e32 v89, v2
	v_mov_b32_e32 v98, v2
	v_mov_b32_e32 v99, v2
	v_mov_b32_e32 v100, v2
	v_mov_b32_e32 v101, v2
	v_mov_b32_e32 v102, v2
	v_mov_b32_e32 v103, v2
	v_mov_b32_e32 v104, v2
	v_mov_b32_e32 v105, v2
	v_mov_b32_e32 v114, v2
	v_mov_b32_e32 v115, v2
	v_mov_b32_e32 v116, v2
	v_mov_b32_e32 v117, v2
	v_mov_b32_e32 v118, v2
	v_mov_b32_e32 v119, v2
	v_mov_b32_e32 v120, v2
	v_mov_b32_e32 v121, v2
	v_mov_b32_e32 v74, v2
	v_mov_b32_e32 v75, v2
	v_mov_b32_e32 v76, v2
	v_mov_b32_e32 v77, v2
	v_mov_b32_e32 v78, v2
	v_mov_b32_e32 v79, v2
	v_mov_b32_e32 v80, v2
	v_mov_b32_e32 v81, v2
	v_mov_b32_e32 v90, v2
	v_mov_b32_e32 v91, v2
	v_mov_b32_e32 v92, v2
	v_mov_b32_e32 v93, v2
	v_mov_b32_e32 v94, v2
	v_mov_b32_e32 v95, v2
	v_mov_b32_e32 v96, v2
	v_mov_b32_e32 v97, v2
	v_mov_b32_e32 v106, v2
	v_mov_b32_e32 v107, v2
	v_mov_b32_e32 v108, v2
	v_mov_b32_e32 v109, v2
	v_mov_b32_e32 v110, v2
	v_mov_b32_e32 v111, v2
	v_mov_b32_e32 v112, v2
	v_mov_b32_e32 v113, v2
	v_mov_b32_e32 v122, v2
	v_mov_b32_e32 v123, v2
	v_mov_b32_e32 v124, v2
	v_mov_b32_e32 v125, v2
	v_mov_b32_e32 v126, v2
	v_mov_b32_e32 v127, v2
	v_mov_b32_e32 v128, v2
	v_mov_b32_e32 v129, v2
	s_cmp_eq_u32 s101, 0
	s_cbranch_scc1 .LBB0_334
	s_add_i32 s66, s20, 2
	s_add_u32 s67, s16, 0x80
	s_addc_u32 s21, s17, 0
	s_add_i32 s72, 0, 0x10000
	s_cmp_eq_u32 s58, s20
	s_cselect_b32 s21, s1, s21
	s_cselect_b32 s20, s0, s67
	v_add_u32_e32 v140, s72, v143
	s_cselect_b32 s71, s15, s65
	s_cselect_b32 s70, s14, s64
	s_add_i32 s67, 0, 0x14000
	ds_read_b128 v[160:163], v140
	ds_read_b128 v[164:167], v140 offset:1024
	ds_read_b128 v[168:171], v140 offset:2048
	ds_read_b128 v[172:175], v140 offset:3072
	v_add_u32_e32 v140, s67, v143
	ds_read_b128 v[176:179], v140
	ds_read_b128 v[180:183], v140 offset:1024
	ds_read_b128 v[184:187], v140 offset:2048
	ds_read_b128 v[188:191], v140 offset:3072
	v_lshl_add_u64 v[140:141], s[16:17], 0, v[136:137]
	s_add_i32 m0, s19, 0xc000
	ds_read_b128 v[192:195], v146
	ds_read_b128 v[196:199], v146 offset:1024
	ds_read_b128 v[200:203], v146 offset:2048
	ds_read_b128 v[204:207], v146 offset:3072
	ds_read_b128 v[208:211], v146 offset:4096
	ds_read_b128 v[212:215], v146 offset:5120
	ds_read_b128 v[216:219], v146 offset:6144
	ds_read_b128 v[220:223], v146 offset:7168
	global_load_lds_dwordx4 v[140:141], off
	v_lshl_add_u64 v[140:141], s[16:17], 0, v[138:139]
	s_add_i32 m0, s19, 0xe000
	s_nop 0
	global_load_lds_dwordx4 v[140:141], off
	s_waitcnt vmcnt(26)
	s_waitcnt lgkmcnt(0)
	s_barrier
	s_waitcnt lgkmcnt(0)
	v_mfma_f32_16x16x32_bf16 v[126:129], v[160:163], v[192:195], v[126:129]
	v_mfma_f32_16x16x32_bf16 v[122:125], v[168:171], v[192:195], v[122:125]
	v_mfma_f32_16x16x32_bf16 v[110:113], v[160:163], v[200:203], v[110:113]
	v_mfma_f32_16x16x32_bf16 v[106:109], v[168:171], v[200:203], v[106:109]
	v_mfma_f32_16x16x32_bf16 v[94:97], v[160:163], v[208:211], v[94:97]
	v_mfma_f32_16x16x32_bf16 v[90:93], v[168:171], v[208:211], v[90:93]
	v_mfma_f32_16x16x32_bf16 v[78:81], v[160:163], v[216:219], v[78:81]
	v_mfma_f32_16x16x32_bf16 v[74:77], v[168:171], v[216:219], v[74:77]
	v_mfma_f32_16x16x32_bf16 v[126:129], v[164:167], v[196:199], v[126:129]
	v_mfma_f32_16x16x32_bf16 v[122:125], v[172:175], v[196:199], v[122:125]
	v_mfma_f32_16x16x32_bf16 v[110:113], v[164:167], v[204:207], v[110:113]
	v_mfma_f32_16x16x32_bf16 v[106:109], v[172:175], v[204:207], v[106:109]
	v_mfma_f32_16x16x32_bf16 v[94:97], v[164:167], v[212:215], v[94:97]
	v_mfma_f32_16x16x32_bf16 v[90:93], v[172:175], v[212:215], v[90:93]
	v_mfma_f32_16x16x32_bf16 v[78:81], v[164:167], v[220:223], v[78:81]
	v_mfma_f32_16x16x32_bf16 v[74:77], v[172:175], v[220:223], v[74:77]
	v_mfma_f32_16x16x32_bf16 v[118:121], v[176:179], v[192:195], v[118:121]
	v_mfma_f32_16x16x32_bf16 v[114:117], v[184:187], v[192:195], v[114:117]
	v_mfma_f32_16x16x32_bf16 v[102:105], v[176:179], v[200:203], v[102:105]
	v_mfma_f32_16x16x32_bf16 v[98:101], v[184:187], v[200:203], v[98:101]
	v_mfma_f32_16x16x32_bf16 v[86:89], v[176:179], v[208:211], v[86:89]
	v_mfma_f32_16x16x32_bf16 v[82:85], v[184:187], v[208:211], v[82:85]
	v_mfma_f32_16x16x32_bf16 v[70:73], v[176:179], v[216:219], v[70:73]
	v_mfma_f32_16x16x32_bf16 v[66:69], v[184:187], v[216:219], v[66:69]
	v_mfma_f32_16x16x32_bf16 v[118:121], v[180:183], v[196:199], v[118:121]
	v_mfma_f32_16x16x32_bf16 v[114:117], v[188:191], v[196:199], v[114:117]
	v_mfma_f32_16x16x32_bf16 v[102:105], v[180:183], v[204:207], v[102:105]
	v_mfma_f32_16x16x32_bf16 v[98:101], v[188:191], v[204:207], v[98:101]
	v_mfma_f32_16x16x32_bf16 v[86:89], v[180:183], v[212:215], v[86:89]
	v_mfma_f32_16x16x32_bf16 v[82:85], v[188:191], v[212:215], v[82:85]
	v_mfma_f32_16x16x32_bf16 v[70:73], v[180:183], v[220:223], v[70:73]
	v_mfma_f32_16x16x32_bf16 v[66:69], v[188:191], v[220:223], v[66:69]
	s_barrier
	s_add_i32 s72, s72, s35
	v_lshl_add_u64 v[140:141], s[70:71], 0, v[0:1]
	s_mov_b32 m0, s72
	ds_read_b128 v[192:195], v146 offset:16384
	ds_read_b128 v[196:199], v146 offset:17408
	ds_read_b128 v[200:203], v146 offset:18432
	ds_read_b128 v[204:207], v146 offset:19456
	ds_read_b128 v[208:211], v146 offset:20480
	ds_read_b128 v[212:215], v146 offset:21504
	ds_read_b128 v[216:219], v146 offset:22528
	ds_read_b128 v[220:223], v146 offset:23552
	global_load_lds_dwordx4 v[140:141], off
	s_add_i32 m0, s72, 0x2000
	v_lshl_add_u64 v[148:149], s[70:71], 0, v[134:135]
	s_add_u32 s70, s70, s80
	s_addc_u32 s71, s71, 0
	s_add_i32 s67, s67, s35
	global_load_lds_dwordx4 v[148:149], off
	v_lshl_add_u64 v[224:225], s[70:71], 0, v[0:1]
	s_mov_b32 m0, s67
	v_lshl_add_u64 v[226:227], s[70:71], 0, v[134:135]
	global_load_lds_dwordx4 v[224:225], off
	s_add_i32 m0, s67, 0x2000
	v_lshl_add_u64 v[228:229], s[20:21], 0, v[130:131]
	global_load_lds_dwordx4 v[226:227], off
	s_mov_b32 m0, s19
	v_lshl_add_u64 v[230:231], s[20:21], 0, v[132:133]
	global_load_lds_dwordx4 v[228:229], off
	s_mov_b32 m0, s29
	s_nop 0
	global_load_lds_dwordx4 v[230:231], off
	s_waitcnt vmcnt(26)
	s_waitcnt lgkmcnt(0)
	s_barrier
	s_waitcnt lgkmcnt(0)
	v_mfma_f32_16x16x32_bf16 v[62:65], v[160:163], v[192:195], v[62:65]
	v_mfma_f32_16x16x32_bf16 v[58:61], v[168:171], v[192:195], v[58:61]
	v_mfma_f32_16x16x32_bf16 v[46:49], v[160:163], v[200:203], v[46:49]
	v_mfma_f32_16x16x32_bf16 v[42:45], v[168:171], v[200:203], v[42:45]
	v_mfma_f32_16x16x32_bf16 v[30:33], v[160:163], v[208:211], v[30:33]
	v_mfma_f32_16x16x32_bf16 v[26:29], v[168:171], v[208:211], v[26:29]
	v_mfma_f32_16x16x32_bf16 v[14:17], v[160:163], v[216:219], v[14:17]
	v_mfma_f32_16x16x32_bf16 v[10:13], v[168:171], v[216:219], v[10:13]
	v_mfma_f32_16x16x32_bf16 v[62:65], v[164:167], v[196:199], v[62:65]
	v_mfma_f32_16x16x32_bf16 v[58:61], v[172:175], v[196:199], v[58:61]
	v_mfma_f32_16x16x32_bf16 v[46:49], v[164:167], v[204:207], v[46:49]
	v_mfma_f32_16x16x32_bf16 v[42:45], v[172:175], v[204:207], v[42:45]
	v_mfma_f32_16x16x32_bf16 v[30:33], v[164:167], v[212:215], v[30:33]
	v_mfma_f32_16x16x32_bf16 v[26:29], v[172:175], v[212:215], v[26:29]
	v_mfma_f32_16x16x32_bf16 v[14:17], v[164:167], v[220:223], v[14:17]
	v_mfma_f32_16x16x32_bf16 v[10:13], v[172:175], v[220:223], v[10:13]
	v_mfma_f32_16x16x32_bf16 v[54:57], v[176:179], v[192:195], v[54:57]
	v_mfma_f32_16x16x32_bf16 v[50:53], v[184:187], v[192:195], v[50:53]
	v_mfma_f32_16x16x32_bf16 v[38:41], v[176:179], v[200:203], v[38:41]
	v_mfma_f32_16x16x32_bf16 v[34:37], v[184:187], v[200:203], v[34:37]
	v_mfma_f32_16x16x32_bf16 v[22:25], v[176:179], v[208:211], v[22:25]
	v_mfma_f32_16x16x32_bf16 v[18:21], v[184:187], v[208:211], v[18:21]
	v_mfma_f32_16x16x32_bf16 v[6:9], v[176:179], v[216:219], v[6:9]
	v_mfma_f32_16x16x32_bf16 v[2:5], v[184:187], v[216:219], v[2:5]
	v_mfma_f32_16x16x32_bf16 v[54:57], v[180:183], v[196:199], v[54:57]
	v_mfma_f32_16x16x32_bf16 v[50:53], v[188:191], v[196:199], v[50:53]
	v_mfma_f32_16x16x32_bf16 v[38:41], v[180:183], v[204:207], v[38:41]
	v_mfma_f32_16x16x32_bf16 v[34:37], v[188:191], v[204:207], v[34:37]
	v_mfma_f32_16x16x32_bf16 v[22:25], v[180:183], v[212:215], v[22:25]
	v_mfma_f32_16x16x32_bf16 v[18:21], v[188:191], v[212:215], v[18:21]
	v_mfma_f32_16x16x32_bf16 v[6:9], v[180:183], v[220:223], v[6:9]
	v_mfma_f32_16x16x32_bf16 v[2:5], v[188:191], v[220:223], v[2:5]
	s_barrier
	s_add_i32 s67, 0, 0x18000
	v_add_u32_e32 v159, s67, v143
	s_add_i32 s70, 0, 0x1c000
	ds_read_b128 v[160:163], v159
	ds_read_b128 v[164:167], v159 offset:1024
	ds_read_b128 v[168:171], v159 offset:2048
	ds_read_b128 v[172:175], v159 offset:3072
	v_add_u32_e32 v159, s70, v143
	ds_read_b128 v[176:179], v159
	ds_read_b128 v[180:183], v159 offset:1024
	ds_read_b128 v[184:187], v159 offset:2048
	ds_read_b128 v[188:191], v159 offset:3072
	s_add_u32 s20, s20, s80
	s_addc_u32 s21, s21, 0
	s_mov_b32 m0, s30
	v_lshl_add_u64 v[232:233], s[20:21], 0, v[130:131]
	ds_read_b128 v[192:195], v146 offset:32768
	ds_read_b128 v[196:199], v146 offset:33792
	ds_read_b128 v[200:203], v146 offset:34816
	ds_read_b128 v[204:207], v146 offset:35840
	ds_read_b128 v[208:211], v146 offset:36864
	ds_read_b128 v[212:215], v146 offset:37888
	ds_read_b128 v[216:219], v146 offset:38912
	ds_read_b128 v[220:223], v146 offset:39936
	global_load_lds_dwordx4 v[232:233], off
	v_lshl_add_u64 v[232:233], s[20:21], 0, v[132:133]
	s_mov_b32 m0, s31
	s_nop 0
	global_load_lds_dwordx4 v[232:233], off
	s_waitcnt vmcnt(8)
	s_waitcnt lgkmcnt(0)
	s_barrier
	s_waitcnt lgkmcnt(0)
	v_mfma_f32_16x16x32_bf16 v[126:129], v[160:163], v[192:195], v[126:129]
	v_mfma_f32_16x16x32_bf16 v[122:125], v[168:171], v[192:195], v[122:125]
	v_mfma_f32_16x16x32_bf16 v[110:113], v[160:163], v[200:203], v[110:113]
	v_mfma_f32_16x16x32_bf16 v[106:109], v[168:171], v[200:203], v[106:109]
	v_mfma_f32_16x16x32_bf16 v[94:97], v[160:163], v[208:211], v[94:97]
	v_mfma_f32_16x16x32_bf16 v[90:93], v[168:171], v[208:211], v[90:93]
	v_mfma_f32_16x16x32_bf16 v[78:81], v[160:163], v[216:219], v[78:81]
	v_mfma_f32_16x16x32_bf16 v[74:77], v[168:171], v[216:219], v[74:77]
	v_mfma_f32_16x16x32_bf16 v[126:129], v[164:167], v[196:199], v[126:129]
	v_mfma_f32_16x16x32_bf16 v[122:125], v[172:175], v[196:199], v[122:125]
	v_mfma_f32_16x16x32_bf16 v[110:113], v[164:167], v[204:207], v[110:113]
	v_mfma_f32_16x16x32_bf16 v[106:109], v[172:175], v[204:207], v[106:109]
	v_mfma_f32_16x16x32_bf16 v[94:97], v[164:167], v[212:215], v[94:97]
	v_mfma_f32_16x16x32_bf16 v[90:93], v[172:175], v[212:215], v[90:93]
	v_mfma_f32_16x16x32_bf16 v[78:81], v[164:167], v[220:223], v[78:81]
	v_mfma_f32_16x16x32_bf16 v[74:77], v[172:175], v[220:223], v[74:77]
	v_mfma_f32_16x16x32_bf16 v[118:121], v[176:179], v[192:195], v[118:121]
	v_mfma_f32_16x16x32_bf16 v[114:117], v[184:187], v[192:195], v[114:117]
	v_mfma_f32_16x16x32_bf16 v[102:105], v[176:179], v[200:203], v[102:105]
	v_mfma_f32_16x16x32_bf16 v[98:101], v[184:187], v[200:203], v[98:101]
	v_mfma_f32_16x16x32_bf16 v[86:89], v[176:179], v[208:211], v[86:89]
	v_mfma_f32_16x16x32_bf16 v[82:85], v[184:187], v[208:211], v[82:85]
	v_mfma_f32_16x16x32_bf16 v[70:73], v[176:179], v[216:219], v[70:73]
	v_mfma_f32_16x16x32_bf16 v[66:69], v[184:187], v[216:219], v[66:69]
	v_mfma_f32_16x16x32_bf16 v[118:121], v[180:183], v[196:199], v[118:121]
	v_mfma_f32_16x16x32_bf16 v[114:117], v[188:191], v[196:199], v[114:117]
	v_mfma_f32_16x16x32_bf16 v[102:105], v[180:183], v[204:207], v[102:105]
	v_mfma_f32_16x16x32_bf16 v[98:101], v[188:191], v[204:207], v[98:101]
	v_mfma_f32_16x16x32_bf16 v[86:89], v[180:183], v[212:215], v[86:89]
	v_mfma_f32_16x16x32_bf16 v[82:85], v[188:191], v[212:215], v[82:85]
	v_mfma_f32_16x16x32_bf16 v[70:73], v[180:183], v[220:223], v[70:73]
	v_mfma_f32_16x16x32_bf16 v[66:69], v[188:191], v[220:223], v[66:69]
	s_barrier
	s_add_i32 s20, s67, s35
	v_lshl_add_u64 v[140:141], v[140:141], 0, s[94:95]
	s_mov_b32 m0, s20
	ds_read_b128 v[192:195], v146 offset:49152
	ds_read_b128 v[196:199], v146 offset:50176
	ds_read_b128 v[200:203], v146 offset:51200
	ds_read_b128 v[204:207], v146 offset:52224
	ds_read_b128 v[208:211], v146 offset:53248
	ds_read_b128 v[212:215], v146 offset:54272
	ds_read_b128 v[216:219], v146 offset:55296
	ds_read_b128 v[220:223], v146 offset:56320
	global_load_lds_dwordx4 v[140:141], off
	v_lshl_add_u64 v[140:141], v[148:149], 0, s[94:95]
	s_add_i32 m0, s20, 0x2000
	s_add_i32 s20, s70, s35
	global_load_lds_dwordx4 v[140:141], off
	v_lshl_add_u64 v[140:141], v[224:225], 0, s[94:95]
	s_mov_b32 m0, s20
	s_nop 0
	global_load_lds_dwordx4 v[140:141], off
	v_lshl_add_u64 v[140:141], v[226:227], 0, s[94:95]
	s_add_i32 m0, s20, 0x2000
	s_nop 0
	global_load_lds_dwordx4 v[140:141], off
	v_lshl_add_u64 v[140:141], v[228:229], 0, s[94:95]
	s_mov_b32 m0, s56
	s_nop 0
	global_load_lds_dwordx4 v[140:141], off
	v_lshl_add_u64 v[140:141], v[230:231], 0, s[94:95]
	s_mov_b32 m0, s57
	s_nop 0
	global_load_lds_dwordx4 v[140:141], off
	s_waitcnt vmcnt(8)
	s_waitcnt lgkmcnt(0)
	s_barrier
	s_waitcnt lgkmcnt(0)
	v_mfma_f32_16x16x32_bf16 v[62:65], v[160:163], v[192:195], v[62:65]
	v_mfma_f32_16x16x32_bf16 v[58:61], v[168:171], v[192:195], v[58:61]
	v_mfma_f32_16x16x32_bf16 v[46:49], v[160:163], v[200:203], v[46:49]
	v_mfma_f32_16x16x32_bf16 v[42:45], v[168:171], v[200:203], v[42:45]
	v_mfma_f32_16x16x32_bf16 v[30:33], v[160:163], v[208:211], v[30:33]
	v_mfma_f32_16x16x32_bf16 v[26:29], v[168:171], v[208:211], v[26:29]
	v_mfma_f32_16x16x32_bf16 v[14:17], v[160:163], v[216:219], v[14:17]
	v_mfma_f32_16x16x32_bf16 v[10:13], v[168:171], v[216:219], v[10:13]
	v_mfma_f32_16x16x32_bf16 v[62:65], v[164:167], v[196:199], v[62:65]
	v_mfma_f32_16x16x32_bf16 v[58:61], v[172:175], v[196:199], v[58:61]
	v_mfma_f32_16x16x32_bf16 v[46:49], v[164:167], v[204:207], v[46:49]
	v_mfma_f32_16x16x32_bf16 v[42:45], v[172:175], v[204:207], v[42:45]
	v_mfma_f32_16x16x32_bf16 v[30:33], v[164:167], v[212:215], v[30:33]
	v_mfma_f32_16x16x32_bf16 v[26:29], v[172:175], v[212:215], v[26:29]
	v_mfma_f32_16x16x32_bf16 v[14:17], v[164:167], v[220:223], v[14:17]
	v_mfma_f32_16x16x32_bf16 v[10:13], v[172:175], v[220:223], v[10:13]
	v_mfma_f32_16x16x32_bf16 v[54:57], v[176:179], v[192:195], v[54:57]
	v_mfma_f32_16x16x32_bf16 v[50:53], v[184:187], v[192:195], v[50:53]
	v_mfma_f32_16x16x32_bf16 v[38:41], v[176:179], v[200:203], v[38:41]
	v_mfma_f32_16x16x32_bf16 v[34:37], v[184:187], v[200:203], v[34:37]
	v_mfma_f32_16x16x32_bf16 v[22:25], v[176:179], v[208:211], v[22:25]
	v_mfma_f32_16x16x32_bf16 v[18:21], v[184:187], v[208:211], v[18:21]
	v_mfma_f32_16x16x32_bf16 v[6:9], v[176:179], v[216:219], v[6:9]
	v_mfma_f32_16x16x32_bf16 v[2:5], v[184:187], v[216:219], v[2:5]
	v_mfma_f32_16x16x32_bf16 v[54:57], v[180:183], v[196:199], v[54:57]
	v_mfma_f32_16x16x32_bf16 v[50:53], v[188:191], v[196:199], v[50:53]
	v_mfma_f32_16x16x32_bf16 v[38:41], v[180:183], v[204:207], v[38:41]
	v_mfma_f32_16x16x32_bf16 v[34:37], v[188:191], v[204:207], v[34:37]
	v_mfma_f32_16x16x32_bf16 v[22:25], v[180:183], v[212:215], v[22:25]
	v_mfma_f32_16x16x32_bf16 v[18:21], v[188:191], v[212:215], v[18:21]
	v_mfma_f32_16x16x32_bf16 v[6:9], v[180:183], v[220:223], v[6:9]
	v_mfma_f32_16x16x32_bf16 v[2:5], v[188:191], v[220:223], v[2:5]
	s_barrier
	s_add_u32 s16, s16, 0x100
	s_addc_u32 s17, s17, 0
	s_add_u32 s64, s64, 0x100
	s_addc_u32 s65, s65, 0
	s_cmp_ge_u32 s66, s55
	s_mov_b32 s20, s66
	s_cbranch_scc0 .LBB0_334
	s_branch .Lkexit_334

.LBB0_337:
	v_and_b32_e32 v234, 15, v150
	v_bfe_u32 v235, v150, 4, 2
	v_lshrrev_b32_e32 v236, 2, v234
	v_and_b32_e32 v234, 3, v234
	v_lshl_or_b32 v235, v236, 2, v235
	v_lshlrev_b32_e32 v234, 3, v234
	v_and_or_b32 v232, v142, -16, v235
	v_lshrrev_b32_e32 v233, 5, v144
	v_lshl_or_b32 v233, v233, 5, v234
	ds_read_b128 v[160:163], v147
	v_lshl_add_u32 v148, s62, 8, v232
	v_ashrrev_i32_e32 v149, 31, v148
	v_mul_lo_u32 v149, s68, v149
	v_mul_lo_u32 v159, s69, v148
	s_waitcnt lgkmcnt(0)
	v_mov_b32_e32 v166, v161
	v_mov_b32_e32 v167, v162
	v_mov_b32_e32 v161, v163
	v_mad_u64_u32 v[164:165], s[16:17], s68, v148, 0
	v_pk_add_f32 v[160:161], v[166:167], v[160:161]
	v_add3_u32 v165, v165, v149, v159
	v_add_f32_e32 v159, v160, v161
	v_fmamk_f32 v159, v159, 0x3a800000, v155
	v_rsq_f32_e32 v159, v159
	v_lshl_add_u64 v[160:161], v[164:165], 1, s[78:79]
	v_lshl_or_b32 v140, s63, 8, v233
	v_ashrrev_i32_e32 v141, 31, v140
	v_mul_f32_e32 v162, v159, v159
	v_max_f32_e32 v165, 0, v129
	v_max_f32_e32 v164, 0, v128
	v_max_f32_e32 v167, 0, v127
	v_max_f32_e32 v166, 0, v126
	v_pk_mul_f32 v[128:129], v[128:129], v[164:165]
	v_max_f32_e32 v165, 0, v125
	v_max_f32_e32 v164, 0, v124
	v_pk_mul_f32 v[126:127], v[126:127], v[166:167]
	v_max_f32_e32 v167, 0, v123
	v_max_f32_e32 v166, 0, v122
	v_pk_mul_f32 v[122:123], v[122:123], v[166:167]
	v_pk_mul_f32 v[124:125], v[124:125], v[164:165]
	v_lshlrev_b64 v[140:141], 1, v[140:141]
	v_pk_mul_f32 v[164:165], v[124:125], v[162:163] op_sel_hi:[1,0]
	v_pk_mul_f32 v[124:125], v[122:123], v[162:163] op_sel_hi:[1,0]
	v_lshl_add_u64 v[160:161], v[160:161], 0, v[140:141]
	v_pk_mul_f32 v[128:129], v[128:129], v[162:163] op_sel_hi:[1,0]
	v_pk_mul_f32 v[126:127], v[126:127], v[162:163] op_sel_hi:[1,0]
	s_and_b64 vcc, exec, s[6:7]
	v_cvt_pk_bf16_f32 v122, v126, v127
	v_cvt_pk_bf16_f32 v123, v128, v129
	v_cvt_pk_bf16_f32 v124, v124, v125
	v_cvt_pk_bf16_f32 v125, v164, v165
	global_store_dwordx4 v[160:161], v[122:125], off
	s_mov_b64 s[6:7], -1
	s_nop 0
	v_max_f32_e32 v123, 0, v121
	v_max_f32_e32 v125, 0, v119
	v_max_f32_e32 v122, 0, v120
	v_max_f32_e32 v124, 0, v118
	v_pk_mul_f32 v[118:119], v[118:119], v[124:125]
	v_pk_mul_f32 v[120:121], v[120:121], v[122:123]
	v_max_f32_e32 v123, 0, v117
	v_max_f32_e32 v125, 0, v115
	v_max_f32_e32 v122, 0, v116
	v_max_f32_e32 v124, 0, v114
	v_pk_mul_f32 v[114:115], v[114:115], v[124:125]
	v_pk_mul_f32 v[116:117], v[116:117], v[122:123]
	v_pk_mul_f32 v[120:121], v[120:121], v[162:163] op_sel_hi:[1,0]
	v_pk_mul_f32 v[122:123], v[116:117], v[162:163] op_sel_hi:[1,0]
	v_pk_mul_f32 v[116:117], v[114:115], v[162:163] op_sel_hi:[1,0]
	v_pk_mul_f32 v[118:119], v[118:119], v[162:163] op_sel_hi:[1,0]
	s_nop 0
	v_cvt_pk_bf16_f32 v114, v118, v119
	v_cvt_pk_bf16_f32 v115, v120, v121
	v_cvt_pk_bf16_f32 v116, v116, v117
	v_cvt_pk_bf16_f32 v117, v122, v123
	global_store_dwordx4 v[160:161], v[114:117], off offset:256
	ds_read_b128 v[114:117], v147 offset:256
	v_or_b32_e32 v118, 16, v148
	v_mul_lo_u32 v122, s69, v118
	v_mad_u64_u32 v[118:119], s[16:17], s68, v118, 0
	s_waitcnt lgkmcnt(0)
	v_mov_b32_e32 v120, v115
	v_mov_b32_e32 v121, v116
	v_mov_b32_e32 v115, v117
	v_pk_add_f32 v[114:115], v[120:121], v[114:115]
	v_add3_u32 v119, v119, v149, v122
	v_add_f32_e32 v114, v114, v115
	v_fmamk_f32 v114, v114, 0x3a800000, v155
	v_rsq_f32_e32 v116, v114
	v_lshl_add_u64 v[114:115], v[118:119], 1, s[78:79]
	v_max_f32_e32 v119, 0, v113
	v_max_f32_e32 v118, 0, v112
	v_max_f32_e32 v121, 0, v111
	v_max_f32_e32 v120, 0, v110
	v_mul_f32_e32 v116, v116, v116
	v_pk_mul_f32 v[110:111], v[110:111], v[120:121]
	v_pk_mul_f32 v[112:113], v[112:113], v[118:119]
	v_pk_mul_f32 v[110:111], v[110:111], v[116:117] op_sel_hi:[1,0]
	v_pk_mul_f32 v[112:113], v[112:113], v[116:117] op_sel_hi:[1,0]
	v_max_f32_e32 v119, 0, v109
	v_max_f32_e32 v118, 0, v108
	v_max_f32_e32 v121, 0, v107
	v_max_f32_e32 v120, 0, v106
	v_pk_mul_f32 v[106:107], v[106:107], v[120:121]
	v_pk_mul_f32 v[108:109], v[108:109], v[118:119]
	v_lshl_add_u64 v[114:115], v[114:115], 0, v[140:141]
	v_pk_mul_f32 v[118:119], v[108:109], v[116:117] op_sel_hi:[1,0]
	v_pk_mul_f32 v[108:109], v[106:107], v[116:117] op_sel_hi:[1,0]
	v_cvt_pk_bf16_f32 v106, v110, v111
	v_cvt_pk_bf16_f32 v107, v112, v113
	s_nop 0
	v_cvt_pk_bf16_f32 v108, v108, v109
	v_cvt_pk_bf16_f32 v109, v118, v119
	global_store_dwordx4 v[114:115], v[106:109], off
	s_nop 1
	v_max_f32_e32 v107, 0, v105
	v_max_f32_e32 v109, 0, v103
	v_max_f32_e32 v106, 0, v104
	v_max_f32_e32 v108, 0, v102
	v_pk_mul_f32 v[102:103], v[102:103], v[108:109]
	v_pk_mul_f32 v[104:105], v[104:105], v[106:107]
	v_max_f32_e32 v107, 0, v101
	v_max_f32_e32 v109, 0, v99
	v_max_f32_e32 v106, 0, v100
	v_max_f32_e32 v108, 0, v98
	v_pk_mul_f32 v[98:99], v[98:99], v[108:109]
	v_pk_mul_f32 v[100:101], v[100:101], v[106:107]
	v_pk_mul_f32 v[104:105], v[104:105], v[116:117] op_sel_hi:[1,0]
	v_pk_mul_f32 v[106:107], v[100:101], v[116:117] op_sel_hi:[1,0]
	v_pk_mul_f32 v[100:101], v[98:99], v[116:117] op_sel_hi:[1,0]
	v_pk_mul_f32 v[102:103], v[102:103], v[116:117] op_sel_hi:[1,0]
	s_nop 0
	v_cvt_pk_bf16_f32 v98, v102, v103
	v_cvt_pk_bf16_f32 v99, v104, v105
	v_cvt_pk_bf16_f32 v100, v100, v101
	v_cvt_pk_bf16_f32 v101, v106, v107
	global_store_dwordx4 v[114:115], v[98:101], off offset:256
	ds_read_b128 v[98:101], v147 offset:512
	v_or_b32_e32 v102, 32, v148
	v_mul_lo_u32 v106, s69, v102
	v_mad_u64_u32 v[102:103], s[16:17], s68, v102, 0
	s_waitcnt lgkmcnt(0)
	v_mov_b32_e32 v104, v99
	v_mov_b32_e32 v105, v100
	v_mov_b32_e32 v99, v101
	v_pk_add_f32 v[98:99], v[104:105], v[98:99]
	v_add3_u32 v103, v103, v149, v106
	v_add_f32_e32 v98, v98, v99
	v_fmamk_f32 v98, v98, 0x3a800000, v155
	v_rsq_f32_e32 v100, v98
	v_lshl_add_u64 v[98:99], v[102:103], 1, s[78:79]
	v_max_f32_e32 v103, 0, v97
	v_max_f32_e32 v102, 0, v96
	v_max_f32_e32 v105, 0, v95
	v_max_f32_e32 v104, 0, v94
	v_mul_f32_e32 v100, v100, v100
	v_pk_mul_f32 v[94:95], v[94:95], v[104:105]
	v_pk_mul_f32 v[96:97], v[96:97], v[102:103]
	v_pk_mul_f32 v[94:95], v[94:95], v[100:101] op_sel_hi:[1,0]
	v_pk_mul_f32 v[96:97], v[96:97], v[100:101] op_sel_hi:[1,0]
	v_max_f32_e32 v103, 0, v93
	v_max_f32_e32 v102, 0, v92
	v_max_f32_e32 v105, 0, v91
	v_max_f32_e32 v104, 0, v90
	v_pk_mul_f32 v[90:91], v[90:91], v[104:105]
	v_pk_mul_f32 v[92:93], v[92:93], v[102:103]
	v_lshl_add_u64 v[98:99], v[98:99], 0, v[140:141]
	v_pk_mul_f32 v[102:103], v[92:93], v[100:101] op_sel_hi:[1,0]
	v_pk_mul_f32 v[92:93], v[90:91], v[100:101] op_sel_hi:[1,0]
	v_cvt_pk_bf16_f32 v90, v94, v95
	v_cvt_pk_bf16_f32 v91, v96, v97
	s_nop 0
	v_cvt_pk_bf16_f32 v92, v92, v93
	v_cvt_pk_bf16_f32 v93, v102, v103
	global_store_dwordx4 v[98:99], v[90:93], off
	s_nop 1
	v_max_f32_e32 v91, 0, v89
	v_max_f32_e32 v93, 0, v87
	v_max_f32_e32 v90, 0, v88
	v_max_f32_e32 v92, 0, v86
	v_pk_mul_f32 v[86:87], v[86:87], v[92:93]
	v_pk_mul_f32 v[88:89], v[88:89], v[90:91]
	v_max_f32_e32 v91, 0, v85
	v_max_f32_e32 v93, 0, v83
	v_max_f32_e32 v90, 0, v84
	v_max_f32_e32 v92, 0, v82
	v_pk_mul_f32 v[82:83], v[82:83], v[92:93]
	v_pk_mul_f32 v[84:85], v[84:85], v[90:91]
	v_pk_mul_f32 v[88:89], v[88:89], v[100:101] op_sel_hi:[1,0]
	v_pk_mul_f32 v[90:91], v[84:85], v[100:101] op_sel_hi:[1,0]
	v_pk_mul_f32 v[84:85], v[82:83], v[100:101] op_sel_hi:[1,0]
	v_pk_mul_f32 v[86:87], v[86:87], v[100:101] op_sel_hi:[1,0]
	s_nop 0
	v_cvt_pk_bf16_f32 v82, v86, v87
	v_cvt_pk_bf16_f32 v83, v88, v89
	v_cvt_pk_bf16_f32 v84, v84, v85
	v_cvt_pk_bf16_f32 v85, v90, v91
	global_store_dwordx4 v[98:99], v[82:85], off offset:256
	ds_read_b128 v[82:85], v147 offset:768
	v_or_b32_e32 v86, 48, v148
	v_mul_lo_u32 v90, s69, v86
	v_mad_u64_u32 v[86:87], s[16:17], s68, v86, 0
	s_waitcnt lgkmcnt(0)
	v_mov_b32_e32 v88, v83
	v_mov_b32_e32 v89, v84
	v_mov_b32_e32 v83, v85
	v_pk_add_f32 v[82:83], v[88:89], v[82:83]
	v_add3_u32 v87, v87, v149, v90
	v_add_f32_e32 v82, v82, v83
	v_fmamk_f32 v82, v82, 0x3a800000, v155
	v_rsq_f32_e32 v84, v82
	v_lshl_add_u64 v[82:83], v[86:87], 1, s[78:79]
	v_max_f32_e32 v87, 0, v81
	v_max_f32_e32 v86, 0, v80
	v_max_f32_e32 v89, 0, v79
	v_max_f32_e32 v88, 0, v78
	v_mul_f32_e32 v84, v84, v84
	v_pk_mul_f32 v[78:79], v[78:79], v[88:89]
	v_pk_mul_f32 v[80:81], v[80:81], v[86:87]
	v_pk_mul_f32 v[78:79], v[78:79], v[84:85] op_sel_hi:[1,0]
	v_pk_mul_f32 v[80:81], v[80:81], v[84:85] op_sel_hi:[1,0]
	v_max_f32_e32 v87, 0, v77
	v_max_f32_e32 v86, 0, v76
	v_max_f32_e32 v89, 0, v75
	v_max_f32_e32 v88, 0, v74
	v_pk_mul_f32 v[74:75], v[74:75], v[88:89]
	v_pk_mul_f32 v[76:77], v[76:77], v[86:87]
	v_lshl_add_u64 v[82:83], v[82:83], 0, v[140:141]
	v_pk_mul_f32 v[86:87], v[76:77], v[84:85] op_sel_hi:[1,0]
	v_pk_mul_f32 v[76:77], v[74:75], v[84:85] op_sel_hi:[1,0]
	v_cvt_pk_bf16_f32 v74, v78, v79
	v_cvt_pk_bf16_f32 v75, v80, v81
	s_nop 0
	v_cvt_pk_bf16_f32 v76, v76, v77
	v_cvt_pk_bf16_f32 v77, v86, v87
	global_store_dwordx4 v[82:83], v[74:77], off
	s_nop 1
	v_max_f32_e32 v75, 0, v73
	v_max_f32_e32 v77, 0, v71
	v_max_f32_e32 v74, 0, v72
	v_max_f32_e32 v76, 0, v70
	v_pk_mul_f32 v[70:71], v[70:71], v[76:77]
	v_pk_mul_f32 v[72:73], v[72:73], v[74:75]
	v_max_f32_e32 v75, 0, v69
	v_max_f32_e32 v77, 0, v67
	v_max_f32_e32 v74, 0, v68
	v_max_f32_e32 v76, 0, v66
	v_pk_mul_f32 v[66:67], v[66:67], v[76:77]
	v_pk_mul_f32 v[68:69], v[68:69], v[74:75]
	v_pk_mul_f32 v[72:73], v[72:73], v[84:85] op_sel_hi:[1,0]
	v_pk_mul_f32 v[74:75], v[68:69], v[84:85] op_sel_hi:[1,0]
	v_pk_mul_f32 v[68:69], v[66:67], v[84:85] op_sel_hi:[1,0]
	v_pk_mul_f32 v[70:71], v[70:71], v[84:85] op_sel_hi:[1,0]
	s_nop 0
	v_cvt_pk_bf16_f32 v66, v70, v71
	v_cvt_pk_bf16_f32 v67, v72, v73
	v_cvt_pk_bf16_f32 v68, v68, v69
	v_cvt_pk_bf16_f32 v69, v74, v75
	global_store_dwordx4 v[82:83], v[66:69], off offset:256
	ds_read_b128 v[66:69], v147 offset:1024
	v_add_u32_e32 v70, 0x80, v148
	v_ashrrev_i32_e32 v71, 31, v70
	v_mul_lo_u32 v74, s68, v71
	v_mul_lo_u32 v75, s69, v70
	s_waitcnt lgkmcnt(0)
	v_mov_b32_e32 v72, v67
	v_mov_b32_e32 v73, v68
	v_mov_b32_e32 v67, v69
	v_pk_add_f32 v[66:67], v[72:73], v[66:67]
	v_mad_u64_u32 v[70:71], s[16:17], s68, v70, 0
	v_add_f32_e32 v66, v66, v67
	v_fmamk_f32 v66, v66, 0x3a800000, v155
	v_add3_u32 v71, v71, v74, v75
	v_rsq_f32_e32 v68, v66
	v_lshl_add_u64 v[66:67], v[70:71], 1, s[78:79]
	v_max_f32_e32 v71, 0, v65
	v_max_f32_e32 v70, 0, v64
	v_max_f32_e32 v73, 0, v63
	v_max_f32_e32 v72, 0, v62
	v_mul_f32_e32 v68, v68, v68
	v_pk_mul_f32 v[62:63], v[62:63], v[72:73]
	v_pk_mul_f32 v[64:65], v[64:65], v[70:71]
	v_pk_mul_f32 v[62:63], v[62:63], v[68:69] op_sel_hi:[1,0]
	v_pk_mul_f32 v[64:65], v[64:65], v[68:69] op_sel_hi:[1,0]
	v_max_f32_e32 v71, 0, v61
	v_max_f32_e32 v70, 0, v60
	v_max_f32_e32 v73, 0, v59
	v_max_f32_e32 v72, 0, v58
	v_pk_mul_f32 v[58:59], v[58:59], v[72:73]
	v_pk_mul_f32 v[60:61], v[60:61], v[70:71]
	v_lshl_add_u64 v[66:67], v[66:67], 0, v[140:141]
	v_pk_mul_f32 v[70:71], v[60:61], v[68:69] op_sel_hi:[1,0]
	v_pk_mul_f32 v[60:61], v[58:59], v[68:69] op_sel_hi:[1,0]
	v_cvt_pk_bf16_f32 v58, v62, v63
	v_cvt_pk_bf16_f32 v59, v64, v65
	s_nop 0
	v_cvt_pk_bf16_f32 v60, v60, v61
	v_cvt_pk_bf16_f32 v61, v70, v71
	global_store_dwordx4 v[66:67], v[58:61], off
	s_nop 1
	v_max_f32_e32 v59, 0, v57
	v_max_f32_e32 v61, 0, v55
	v_max_f32_e32 v58, 0, v56
	v_max_f32_e32 v60, 0, v54
	v_pk_mul_f32 v[54:55], v[54:55], v[60:61]
	v_pk_mul_f32 v[56:57], v[56:57], v[58:59]
	v_max_f32_e32 v59, 0, v53
	v_max_f32_e32 v61, 0, v51
	v_max_f32_e32 v58, 0, v52
	v_max_f32_e32 v60, 0, v50
	v_pk_mul_f32 v[50:51], v[50:51], v[60:61]
	v_pk_mul_f32 v[52:53], v[52:53], v[58:59]
	v_pk_mul_f32 v[56:57], v[56:57], v[68:69] op_sel_hi:[1,0]
	v_pk_mul_f32 v[58:59], v[52:53], v[68:69] op_sel_hi:[1,0]
	v_pk_mul_f32 v[52:53], v[50:51], v[68:69] op_sel_hi:[1,0]
	v_pk_mul_f32 v[54:55], v[54:55], v[68:69] op_sel_hi:[1,0]
	s_nop 0
	v_cvt_pk_bf16_f32 v50, v54, v55
	v_cvt_pk_bf16_f32 v51, v56, v57
	v_cvt_pk_bf16_f32 v52, v52, v53
	v_cvt_pk_bf16_f32 v53, v58, v59
	global_store_dwordx4 v[66:67], v[50:53], off offset:256
	ds_read_b128 v[50:53], v147 offset:1280
	v_add_u32_e32 v54, 0x90, v148
	v_ashrrev_i32_e32 v55, 31, v54
	v_mul_lo_u32 v58, s68, v55
	v_mul_lo_u32 v59, s69, v54
	s_waitcnt lgkmcnt(0)
	v_mov_b32_e32 v56, v51
	v_mov_b32_e32 v57, v52
	v_mov_b32_e32 v51, v53
	v_pk_add_f32 v[50:51], v[56:57], v[50:51]
	v_mad_u64_u32 v[54:55], s[16:17], s68, v54, 0
	v_add_f32_e32 v50, v50, v51
	v_fmamk_f32 v50, v50, 0x3a800000, v155
	v_add3_u32 v55, v55, v58, v59
	v_rsq_f32_e32 v52, v50
	v_lshl_add_u64 v[50:51], v[54:55], 1, s[78:79]
	v_max_f32_e32 v55, 0, v49
	v_max_f32_e32 v54, 0, v48
	v_max_f32_e32 v57, 0, v47
	v_max_f32_e32 v56, 0, v46
	v_mul_f32_e32 v52, v52, v52
	v_pk_mul_f32 v[46:47], v[46:47], v[56:57]
	v_pk_mul_f32 v[48:49], v[48:49], v[54:55]
	v_pk_mul_f32 v[46:47], v[46:47], v[52:53] op_sel_hi:[1,0]
	v_pk_mul_f32 v[48:49], v[48:49], v[52:53] op_sel_hi:[1,0]
	v_max_f32_e32 v55, 0, v45
	v_max_f32_e32 v54, 0, v44
	v_max_f32_e32 v57, 0, v43
	v_max_f32_e32 v56, 0, v42
	v_pk_mul_f32 v[42:43], v[42:43], v[56:57]
	v_pk_mul_f32 v[44:45], v[44:45], v[54:55]
	v_lshl_add_u64 v[50:51], v[50:51], 0, v[140:141]
	v_pk_mul_f32 v[54:55], v[44:45], v[52:53] op_sel_hi:[1,0]
	v_pk_mul_f32 v[44:45], v[42:43], v[52:53] op_sel_hi:[1,0]
	v_cvt_pk_bf16_f32 v42, v46, v47
	v_cvt_pk_bf16_f32 v43, v48, v49
	s_nop 0
	v_cvt_pk_bf16_f32 v44, v44, v45
	v_cvt_pk_bf16_f32 v45, v54, v55
	global_store_dwordx4 v[50:51], v[42:45], off
	s_nop 1
	v_max_f32_e32 v43, 0, v41
	v_max_f32_e32 v45, 0, v39
	v_max_f32_e32 v42, 0, v40
	v_max_f32_e32 v44, 0, v38
	v_pk_mul_f32 v[38:39], v[38:39], v[44:45]
	v_pk_mul_f32 v[40:41], v[40:41], v[42:43]
	v_max_f32_e32 v43, 0, v37
	v_max_f32_e32 v45, 0, v35
	v_max_f32_e32 v42, 0, v36
	v_max_f32_e32 v44, 0, v34
	v_pk_mul_f32 v[34:35], v[34:35], v[44:45]
	v_pk_mul_f32 v[36:37], v[36:37], v[42:43]
	v_pk_mul_f32 v[40:41], v[40:41], v[52:53] op_sel_hi:[1,0]
	v_pk_mul_f32 v[42:43], v[36:37], v[52:53] op_sel_hi:[1,0]
	v_pk_mul_f32 v[36:37], v[34:35], v[52:53] op_sel_hi:[1,0]
	v_pk_mul_f32 v[38:39], v[38:39], v[52:53] op_sel_hi:[1,0]
	s_nop 0
	v_cvt_pk_bf16_f32 v34, v38, v39
	v_cvt_pk_bf16_f32 v35, v40, v41
	v_cvt_pk_bf16_f32 v36, v36, v37
	v_cvt_pk_bf16_f32 v37, v42, v43
	global_store_dwordx4 v[50:51], v[34:37], off offset:256
	ds_read_b128 v[34:37], v147 offset:1536
	v_add_u32_e32 v38, 0xa0, v148
	v_ashrrev_i32_e32 v39, 31, v38
	v_mul_lo_u32 v42, s68, v39
	v_mul_lo_u32 v43, s69, v38
	s_waitcnt lgkmcnt(0)
	v_mov_b32_e32 v40, v35
	v_mov_b32_e32 v41, v36
	v_mov_b32_e32 v35, v37
	v_pk_add_f32 v[34:35], v[40:41], v[34:35]
	v_mad_u64_u32 v[38:39], s[16:17], s68, v38, 0
	v_add_f32_e32 v34, v34, v35
	v_fmamk_f32 v34, v34, 0x3a800000, v155
	v_add3_u32 v39, v39, v42, v43
	v_rsq_f32_e32 v36, v34
	v_lshl_add_u64 v[34:35], v[38:39], 1, s[78:79]
	v_max_f32_e32 v39, 0, v33
	v_max_f32_e32 v38, 0, v32
	v_max_f32_e32 v41, 0, v31
	v_max_f32_e32 v40, 0, v30
	v_mul_f32_e32 v36, v36, v36
	v_pk_mul_f32 v[30:31], v[30:31], v[40:41]
	v_pk_mul_f32 v[32:33], v[32:33], v[38:39]
	v_pk_mul_f32 v[30:31], v[30:31], v[36:37] op_sel_hi:[1,0]
	v_pk_mul_f32 v[32:33], v[32:33], v[36:37] op_sel_hi:[1,0]
	v_max_f32_e32 v39, 0, v29
	v_max_f32_e32 v38, 0, v28
	v_max_f32_e32 v41, 0, v27
	v_max_f32_e32 v40, 0, v26
	v_pk_mul_f32 v[26:27], v[26:27], v[40:41]
	v_pk_mul_f32 v[28:29], v[28:29], v[38:39]
	v_lshl_add_u64 v[34:35], v[34:35], 0, v[140:141]
	v_pk_mul_f32 v[38:39], v[28:29], v[36:37] op_sel_hi:[1,0]
	v_pk_mul_f32 v[28:29], v[26:27], v[36:37] op_sel_hi:[1,0]
	v_cvt_pk_bf16_f32 v26, v30, v31
	v_cvt_pk_bf16_f32 v27, v32, v33
	s_nop 0
	v_cvt_pk_bf16_f32 v28, v28, v29
	v_cvt_pk_bf16_f32 v29, v38, v39
	global_store_dwordx4 v[34:35], v[26:29], off
	s_nop 1
	v_max_f32_e32 v27, 0, v25
	v_max_f32_e32 v29, 0, v23
	v_max_f32_e32 v26, 0, v24
	v_max_f32_e32 v28, 0, v22
	v_pk_mul_f32 v[22:23], v[22:23], v[28:29]
	v_pk_mul_f32 v[24:25], v[24:25], v[26:27]
	v_max_f32_e32 v27, 0, v21
	v_max_f32_e32 v29, 0, v19
	v_max_f32_e32 v26, 0, v20
	v_max_f32_e32 v28, 0, v18
	v_pk_mul_f32 v[18:19], v[18:19], v[28:29]
	v_pk_mul_f32 v[20:21], v[20:21], v[26:27]
	v_pk_mul_f32 v[24:25], v[24:25], v[36:37] op_sel_hi:[1,0]
	v_pk_mul_f32 v[26:27], v[20:21], v[36:37] op_sel_hi:[1,0]
	v_pk_mul_f32 v[20:21], v[18:19], v[36:37] op_sel_hi:[1,0]
	v_pk_mul_f32 v[22:23], v[22:23], v[36:37] op_sel_hi:[1,0]
	s_nop 0
	v_cvt_pk_bf16_f32 v18, v22, v23
	v_cvt_pk_bf16_f32 v19, v24, v25
	v_cvt_pk_bf16_f32 v20, v20, v21
	v_cvt_pk_bf16_f32 v21, v26, v27
	global_store_dwordx4 v[34:35], v[18:21], off offset:256
	ds_read_b128 v[18:21], v147 offset:1792
	v_add_u32_e32 v22, 0xb0, v148
	v_ashrrev_i32_e32 v23, 31, v22
	v_mul_lo_u32 v26, s68, v23
	v_mul_lo_u32 v27, s69, v22
	s_waitcnt lgkmcnt(0)
	v_mov_b32_e32 v24, v19
	v_mov_b32_e32 v25, v20
	v_mov_b32_e32 v19, v21
	v_pk_add_f32 v[18:19], v[24:25], v[18:19]
	v_mad_u64_u32 v[22:23], s[16:17], s68, v22, 0
	v_add_f32_e32 v18, v18, v19
	v_fmamk_f32 v18, v18, 0x3a800000, v155
	v_add3_u32 v23, v23, v26, v27
	v_rsq_f32_e32 v20, v18
	v_lshl_add_u64 v[18:19], v[22:23], 1, s[78:79]
	v_max_f32_e32 v23, 0, v17
	v_max_f32_e32 v22, 0, v16
	v_max_f32_e32 v25, 0, v15
	v_max_f32_e32 v24, 0, v14
	v_mul_f32_e32 v20, v20, v20
	v_pk_mul_f32 v[14:15], v[14:15], v[24:25]
	v_pk_mul_f32 v[16:17], v[16:17], v[22:23]
	v_pk_mul_f32 v[14:15], v[14:15], v[20:21] op_sel_hi:[1,0]
	v_pk_mul_f32 v[16:17], v[16:17], v[20:21] op_sel_hi:[1,0]
	v_max_f32_e32 v23, 0, v13
	v_max_f32_e32 v22, 0, v12
	v_max_f32_e32 v25, 0, v11
	v_max_f32_e32 v24, 0, v10
	v_pk_mul_f32 v[10:11], v[10:11], v[24:25]
	v_pk_mul_f32 v[12:13], v[12:13], v[22:23]
	v_lshl_add_u64 v[18:19], v[18:19], 0, v[140:141]
	v_pk_mul_f32 v[22:23], v[12:13], v[20:21] op_sel_hi:[1,0]
	v_pk_mul_f32 v[12:13], v[10:11], v[20:21] op_sel_hi:[1,0]
	v_cvt_pk_bf16_f32 v10, v14, v15
	v_cvt_pk_bf16_f32 v11, v16, v17
	s_nop 0
	v_cvt_pk_bf16_f32 v12, v12, v13
	v_cvt_pk_bf16_f32 v13, v22, v23
	global_store_dwordx4 v[18:19], v[10:13], off
	s_nop 1
	v_max_f32_e32 v11, 0, v9
	v_max_f32_e32 v13, 0, v7
	v_max_f32_e32 v10, 0, v8
	v_max_f32_e32 v12, 0, v6
	v_pk_mul_f32 v[6:7], v[6:7], v[12:13]
	v_pk_mul_f32 v[8:9], v[8:9], v[10:11]
	v_max_f32_e32 v11, 0, v5
	v_max_f32_e32 v13, 0, v3
	v_max_f32_e32 v10, 0, v4
	v_max_f32_e32 v12, 0, v2
	v_pk_mul_f32 v[2:3], v[2:3], v[12:13]
	v_pk_mul_f32 v[4:5], v[4:5], v[10:11]
	v_pk_mul_f32 v[8:9], v[8:9], v[20:21] op_sel_hi:[1,0]
	v_pk_mul_f32 v[10:11], v[4:5], v[20:21] op_sel_hi:[1,0]
	v_pk_mul_f32 v[4:5], v[2:3], v[20:21] op_sel_hi:[1,0]
	v_pk_mul_f32 v[6:7], v[6:7], v[20:21] op_sel_hi:[1,0]
	s_nop 0
	v_cvt_pk_bf16_f32 v2, v6, v7
	v_cvt_pk_bf16_f32 v3, v8, v9
	v_cvt_pk_bf16_f32 v4, v4, v5
	v_cvt_pk_bf16_f32 v5, v10, v11
	global_store_dwordx4 v[18:19], v[2:5], off offset:256
	s_cbranch_vccnz .LBB0_325
	s_mov_b32 s101, 1
	s_nop 0
	v_lshl_add_u32 v2, s61, 8, v145
	v_ashrrev_i32_e32 v3, 31, v2
	s_mov_b32 m0, s18
	v_lshl_add_u64 v[2:3], v[2:3], 4, s[96:97]
	s_mov_b64 s[6:7], 0x800
	global_load_lds_dwordx4 v[2:3], off
	v_lshl_add_u64 v[2:3], v[2:3], 0, s[6:7]
	s_add_i32 m0, s18, 0x400
	s_andn2_b64 vcc, exec, s[8:9]
	global_load_lds_dwordx4 v[2:3], off
	s_cbranch_vccnz .LBB0_324
	s_barrier
	s_branch .LBB0_324

.LBB0_349:
	s_add_i32 m0, s23, 0x18000
	v_lshl_add_u64 v[2:3], v[2:3], 0, s[94:95]
	s_waitcnt vmcnt(2)
	s_barrier
	global_load_lds_dwordx4 v[2:3], off
	v_lshl_add_u64 v[2:3], v[4:5], 0, s[94:95]
	s_add_i32 m0, s23, 0x1a000
	s_add_i32 s56, s23, 0x8000
	global_load_lds_dwordx4 v[2:3], off
	v_lshl_add_u64 v[2:3], v[10:11], 0, s[94:95]
	s_mov_b32 m0, s56
	s_add_i32 s57, s23, 0xa000
	global_load_lds_dwordx4 v[2:3], off
	v_lshl_add_u64 v[2:3], v[12:13], 0, s[94:95]
	s_mov_b32 m0, s57
	v_or_b32_e32 v159, s5, v21
	global_load_lds_dwordx4 v[2:3], off
	s_add_i32 m0, s23, 0x1c000
	v_lshl_add_u64 v[2:3], v[6:7], 0, s[94:95]
	global_load_lds_dwordx4 v[2:3], off
	v_lshl_add_u64 v[2:3], v[8:9], 0, s[94:95]
	s_add_i32 m0, s23, 0x1e000
	v_lshlrev_b32_e32 v24, 6, v159
	global_load_lds_dwordx4 v[2:3], off
	s_movk_i32 s5, 0x3c0
	v_lshlrev_b32_e32 v25, 2, v159
	s_lshr_b32 s55, s13, 6
	v_and_or_b32 v24, v24, s5, v22
	v_and_b32_e32 v25, 32, v25
	v_bitop3_b32 v24, v24, s1, v25 bitop3:0xde
	s_lshl_b32 s1, s0, 12
	v_lshlrev_b32_e32 v26, 2, v21
	s_add_i32 s58, s55, -2
	v_lshlrev_b32_e32 v23, 3, v20
	v_lshl_or_b32 v25, v21, 6, v22
	v_and_b32_e32 v26, 32, v26
	s_cmpk_lt_u32 s4, 0x100
	v_or_b32_e32 v2, s0, v20
	v_bitop3_b32 v160, v25, s1, v26 bitop3:0xde
	v_lshl_or_b32 v161, s0, 5, v23
	s_cselect_b64 s[14:15], -1, 0
	s_lshl_b32 s60, s0, 3
	v_cmp_eq_u32_e64 s[0:1], 0, v2
	v_mov_b32_e32 v3, v1
	s_waitcnt vmcnt(6)
	v_or_b32_e32 v164, 16, v159
	v_writelane_b32 v248, s0, 24
	v_or_b32_e32 v165, 32, v159
	v_or_b32_e32 v166, 48, v159
	v_writelane_b32 v248, s1, 25
	v_add_u32_e32 v167, 0x90, v159
	v_readlane_b32 s0, v248, 42
	s_lshl_b32 s62, s0, 2
	v_cvt_f32_u32_e32 v2, s62
	s_sub_i32 s0, 0, s62
	v_add_u32_e32 v168, 0xa0, v159
	v_add_u32_e32 v169, 0xb0, v159
	v_rcp_iflag_f32_e32 v2, v2
	v_lshlrev_b32_e32 v4, 4, v21
	v_add_u32_e32 v163, 0x80, v159
	v_lshlrev_b32_e32 v5, 5, v164
	v_mul_f32_e32 v2, 0x4f7ffffe, v2
	v_cvt_u32_f32_e32 v2, v2
	v_lshlrev_b32_e32 v6, 5, v165
	v_lshlrev_b32_e32 v7, 5, v166
	v_lshlrev_b32_e32 v8, 5, v167
	v_readfirstlane_b32 s1, v2
	v_add_u32_e32 v2, v16, v14
	v_add_lshl_u32 v2, v2, v15, 1
	v_mov_b32_e32 v2, v246
	s_mul_i32 s0, s0, s1
	v_lshl_add_u64 v[136:137], s[16:17], 0, v[2:3]
	v_add_u32_e32 v2, v19, v17
	v_lshlrev_b32_e32 v9, 5, v168
	v_lshlrev_b32_e32 v10, 5, v169
	v_readlane_b32 s6, v249, 46
	s_mul_hi_u32 s0, s1, s0
	v_add_lshl_u32 v2, v2, v18, 1
	v_mov_b32_e32 v2, v247
	v_or_b32_e32 v162, v159, v22
	s_mov_b32 s59, 0
	v_cmp_eq_u32_e64 s[4:5], 0, v20
	s_mov_b32 s13, s81
	s_lshr_b32 s61, s12, 3
	v_lshl_add_u32 v170, v159, 5, s6
	v_lshl_add_u32 v171, v163, 5, s6
	s_add_i32 s63, s1, s0
	v_lshl_add_u64 v[138:139], s[16:17], 0, v[2:3]
	v_add_u32_e32 v172, 0, v24
	v_lshrrev_b32_e32 v245, 10, v172
	v_lshl_or_b32 v172, v245, 10, v243
	v_add_u32_e32 v173, s21, v4
	v_add_u32_e32 v174, s6, v5
	v_add_u32_e32 v175, s6, v6
	v_add_u32_e32 v176, s6, v7
	v_add_u32_e32 v177, s6, v8
	v_add_u32_e32 v178, s6, v9
	v_add_u32_e32 v179, s6, v10
	s_mov_b32 s72, 0x3e6d3388
	s_mov_b32 s90, 0xbf3a00e3
	s_barrier
	s_mov_b32 s101, 0
	s_branch .LBB0_352

.LBB0_359:
	s_add_u32 s2, s2, 0x80
	s_addc_u32 s3, s3, 0
	s_add_u32 s19, s10, 0x100
	v_mov_b32_e32 v2, 0
	s_addc_u32 s29, s11, 0
	s_mov_b32 s10, 0
	v_mov_b32_e32 v3, v2
	s_waitcnt lgkmcnt(0)
	v_mov_b32_e32 v4, v2
	v_mov_b32_e32 v5, v2
	v_mov_b32_e32 v6, v2
	v_mov_b32_e32 v7, v2
	v_mov_b32_e32 v8, v2
	v_mov_b32_e32 v9, v2
	v_mov_b32_e32 v18, v2
	v_mov_b32_e32 v19, v2
	v_mov_b32_e32 v20, v2
	v_mov_b32_e32 v21, v2
	v_mov_b32_e32 v22, v2
	v_mov_b32_e32 v23, v2
	v_mov_b32_e32 v24, v2
	v_mov_b32_e32 v25, v2
	v_mov_b32_e32 v34, v2
	v_mov_b32_e32 v35, v2
	v_mov_b32_e32 v36, v2
	v_mov_b32_e32 v37, v2
	v_mov_b32_e32 v38, v2
	v_mov_b32_e32 v39, v2
	v_mov_b32_e32 v40, v2
	v_mov_b32_e32 v41, v2
	v_mov_b32_e32 v50, v2
	v_mov_b32_e32 v51, v2
	v_mov_b32_e32 v52, v2
	v_mov_b32_e32 v53, v2
	v_mov_b32_e32 v54, v2
	v_mov_b32_e32 v55, v2
	v_mov_b32_e32 v56, v2
	v_mov_b32_e32 v57, v2
	v_mov_b32_e32 v10, v2
	v_mov_b32_e32 v11, v2
	v_mov_b32_e32 v12, v2
	v_mov_b32_e32 v13, v2
	v_mov_b32_e32 v14, v2
	v_mov_b32_e32 v15, v2
	v_mov_b32_e32 v16, v2
	v_mov_b32_e32 v17, v2
	v_mov_b32_e32 v26, v2
	v_mov_b32_e32 v27, v2
	v_mov_b32_e32 v28, v2
	v_mov_b32_e32 v29, v2
	v_mov_b32_e32 v30, v2
	v_mov_b32_e32 v31, v2
	v_mov_b32_e32 v32, v2
	v_mov_b32_e32 v33, v2
	v_mov_b32_e32 v42, v2
	v_mov_b32_e32 v43, v2
	v_mov_b32_e32 v44, v2
	v_mov_b32_e32 v45, v2
	v_mov_b32_e32 v46, v2
	v_mov_b32_e32 v47, v2
	v_mov_b32_e32 v48, v2
	v_mov_b32_e32 v49, v2
	v_mov_b32_e32 v58, v2
	v_mov_b32_e32 v59, v2
	v_mov_b32_e32 v60, v2
	v_mov_b32_e32 v61, v2
	v_mov_b32_e32 v62, v2
	v_mov_b32_e32 v63, v2
	v_mov_b32_e32 v64, v2
	v_mov_b32_e32 v65, v2
	v_mov_b32_e32 v66, v2
	v_mov_b32_e32 v67, v2
	v_mov_b32_e32 v68, v2
	v_mov_b32_e32 v69, v2
	v_mov_b32_e32 v70, v2
	v_mov_b32_e32 v71, v2
	v_mov_b32_e32 v72, v2
	v_mov_b32_e32 v73, v2
	v_mov_b32_e32 v82, v2
	v_mov_b32_e32 v83, v2
	v_mov_b32_e32 v84, v2
	v_mov_b32_e32 v85, v2
	v_mov_b32_e32 v86, v2
	v_mov_b32_e32 v87, v2
	v_mov_b32_e32 v88, v2
	v_mov_b32_e32 v89, v2
	v_mov_b32_e32 v98, v2
	v_mov_b32_e32 v99, v2
	v_mov_b32_e32 v100, v2
	v_mov_b32_e32 v101, v2
	v_mov_b32_e32 v102, v2
	v_mov_b32_e32 v103, v2
	v_mov_b32_e32 v104, v2
	v_mov_b32_e32 v105, v2
	v_mov_b32_e32 v114, v2
	v_mov_b32_e32 v115, v2
	v_mov_b32_e32 v116, v2
	v_mov_b32_e32 v117, v2
	v_mov_b32_e32 v118, v2
	v_mov_b32_e32 v119, v2
	v_mov_b32_e32 v120, v2
	v_mov_b32_e32 v121, v2
	v_mov_b32_e32 v74, v2
	v_mov_b32_e32 v75, v2
	v_mov_b32_e32 v76, v2
	v_mov_b32_e32 v77, v2
	v_mov_b32_e32 v78, v2
	v_mov_b32_e32 v79, v2
	v_mov_b32_e32 v80, v2
	v_mov_b32_e32 v81, v2
	v_mov_b32_e32 v90, v2
	v_mov_b32_e32 v91, v2
	v_mov_b32_e32 v92, v2
	v_mov_b32_e32 v93, v2
	v_mov_b32_e32 v94, v2
	v_mov_b32_e32 v95, v2
	v_mov_b32_e32 v96, v2
	v_mov_b32_e32 v97, v2
	v_mov_b32_e32 v106, v2
	v_mov_b32_e32 v107, v2
	v_mov_b32_e32 v108, v2
	v_mov_b32_e32 v109, v2
	v_mov_b32_e32 v110, v2
	v_mov_b32_e32 v111, v2
	v_mov_b32_e32 v112, v2
	v_mov_b32_e32 v113, v2
	v_mov_b32_e32 v122, v2
	v_mov_b32_e32 v123, v2
	v_mov_b32_e32 v124, v2
	v_mov_b32_e32 v125, v2
	v_mov_b32_e32 v126, v2
	v_mov_b32_e32 v127, v2
	v_mov_b32_e32 v128, v2
	v_mov_b32_e32 v129, v2
	s_cmp_eq_u32 s101, 0
	s_cbranch_scc1 .LBB0_360
	s_add_i32 s30, s10, 2
	s_add_u32 s31, s2, 0x80
	s_addc_u32 s11, s3, 0
	s_add_i32 s35, 0, 0x10000
	s_cmp_eq_u32 s58, s10
	s_cselect_b32 s11, s1, s11
	s_cselect_b32 s10, s0, s31
	v_add_u32_e32 v148, s35, v160
	s_cselect_b32 s67, s7, s29
	s_cselect_b32 s66, s6, s19
	s_add_i32 s31, 0, 0x14000
	ds_read_b128 v[140:143], v148
	ds_read_b128 v[144:147], v148 offset:1024
	ds_read_b128 v[180:183], v148 offset:2048
	ds_read_b128 v[184:187], v148 offset:3072
	v_add_u32_e32 v148, s31, v160
	ds_read_b128 v[188:191], v148
	ds_read_b128 v[192:195], v148 offset:1024
	ds_read_b128 v[196:199], v148 offset:2048
	ds_read_b128 v[200:203], v148 offset:3072
	v_lshl_add_u64 v[148:149], s[2:3], 0, v[136:137]
	s_add_i32 m0, s23, 0xc000
	ds_read_b128 v[204:207], v172
	ds_read_b128 v[208:211], v172 offset:1024
	ds_read_b128 v[212:215], v172 offset:2048
	ds_read_b128 v[216:219], v172 offset:3072
	ds_read_b128 v[220:223], v172 offset:4096
	ds_read_b128 v[224:227], v172 offset:5120
	ds_read_b128 v[228:231], v172 offset:6144
	ds_read_b128 v[232:235], v172 offset:7168
	global_load_lds_dwordx4 v[148:149], off
	v_lshl_add_u64 v[148:149], s[2:3], 0, v[138:139]
	s_add_i32 m0, s23, 0xe000
	s_nop 0
	global_load_lds_dwordx4 v[148:149], off
	s_waitcnt vmcnt(26)
	s_waitcnt lgkmcnt(0)
	s_barrier
	s_waitcnt lgkmcnt(0)
	v_mfma_f32_16x16x32_bf16 v[126:129], v[140:143], v[204:207], v[126:129]
	v_mfma_f32_16x16x32_bf16 v[122:125], v[180:183], v[204:207], v[122:125]
	v_mfma_f32_16x16x32_bf16 v[110:113], v[140:143], v[212:215], v[110:113]
	v_mfma_f32_16x16x32_bf16 v[106:109], v[180:183], v[212:215], v[106:109]
	v_mfma_f32_16x16x32_bf16 v[94:97], v[140:143], v[220:223], v[94:97]
	v_mfma_f32_16x16x32_bf16 v[90:93], v[180:183], v[220:223], v[90:93]
	v_mfma_f32_16x16x32_bf16 v[78:81], v[140:143], v[228:231], v[78:81]
	v_mfma_f32_16x16x32_bf16 v[74:77], v[180:183], v[228:231], v[74:77]
	v_mfma_f32_16x16x32_bf16 v[126:129], v[144:147], v[208:211], v[126:129]
	v_mfma_f32_16x16x32_bf16 v[122:125], v[184:187], v[208:211], v[122:125]
	v_mfma_f32_16x16x32_bf16 v[110:113], v[144:147], v[216:219], v[110:113]
	v_mfma_f32_16x16x32_bf16 v[106:109], v[184:187], v[216:219], v[106:109]
	v_mfma_f32_16x16x32_bf16 v[94:97], v[144:147], v[224:227], v[94:97]
	v_mfma_f32_16x16x32_bf16 v[90:93], v[184:187], v[224:227], v[90:93]
	v_mfma_f32_16x16x32_bf16 v[78:81], v[144:147], v[232:235], v[78:81]
	v_mfma_f32_16x16x32_bf16 v[74:77], v[184:187], v[232:235], v[74:77]
	v_mfma_f32_16x16x32_bf16 v[118:121], v[188:191], v[204:207], v[118:121]
	v_mfma_f32_16x16x32_bf16 v[114:117], v[196:199], v[204:207], v[114:117]
	v_mfma_f32_16x16x32_bf16 v[102:105], v[188:191], v[212:215], v[102:105]
	v_mfma_f32_16x16x32_bf16 v[98:101], v[196:199], v[212:215], v[98:101]
	v_mfma_f32_16x16x32_bf16 v[86:89], v[188:191], v[220:223], v[86:89]
	v_mfma_f32_16x16x32_bf16 v[82:85], v[196:199], v[220:223], v[82:85]
	v_mfma_f32_16x16x32_bf16 v[70:73], v[188:191], v[228:231], v[70:73]
	v_mfma_f32_16x16x32_bf16 v[66:69], v[196:199], v[228:231], v[66:69]
	v_mfma_f32_16x16x32_bf16 v[118:121], v[192:195], v[208:211], v[118:121]
	v_mfma_f32_16x16x32_bf16 v[114:117], v[200:203], v[208:211], v[114:117]
	v_mfma_f32_16x16x32_bf16 v[102:105], v[192:195], v[216:219], v[102:105]
	v_mfma_f32_16x16x32_bf16 v[98:101], v[200:203], v[216:219], v[98:101]
	v_mfma_f32_16x16x32_bf16 v[86:89], v[192:195], v[224:227], v[86:89]
	v_mfma_f32_16x16x32_bf16 v[82:85], v[200:203], v[224:227], v[82:85]
	v_mfma_f32_16x16x32_bf16 v[70:73], v[192:195], v[232:235], v[70:73]
	v_mfma_f32_16x16x32_bf16 v[66:69], v[200:203], v[232:235], v[66:69]
	s_barrier
	s_add_i32 s35, s35, s20
	v_lshl_add_u64 v[148:149], s[66:67], 0, v[0:1]
	s_mov_b32 m0, s35
	ds_read_b128 v[204:207], v172 offset:16384
	ds_read_b128 v[208:211], v172 offset:17408
	ds_read_b128 v[212:215], v172 offset:18432
	ds_read_b128 v[216:219], v172 offset:19456
	ds_read_b128 v[220:223], v172 offset:20480
	ds_read_b128 v[224:227], v172 offset:21504
	ds_read_b128 v[228:231], v172 offset:22528
	ds_read_b128 v[232:235], v172 offset:23552
	global_load_lds_dwordx4 v[148:149], off
	s_add_i32 m0, s35, 0x2000
	v_lshl_add_u64 v[236:237], s[66:67], 0, v[134:135]
	s_add_u32 s66, s66, s16
	s_addc_u32 s67, s67, 0
	s_add_i32 s31, s31, s20
	global_load_lds_dwordx4 v[236:237], off
	v_lshl_add_u64 v[238:239], s[66:67], 0, v[0:1]
	s_mov_b32 m0, s31
	v_lshl_add_u64 v[240:241], s[66:67], 0, v[134:135]
	global_load_lds_dwordx4 v[238:239], off
	s_add_i32 m0, s31, 0x2000
	v_lshl_add_u64 v[242:243], s[10:11], 0, v[130:131]
	global_load_lds_dwordx4 v[240:241], off
	s_mov_b32 m0, s23
	v_lshl_add_u64 v[244:245], s[10:11], 0, v[132:133]
	global_load_lds_dwordx4 v[242:243], off
	s_mov_b32 m0, s52
	s_nop 0
	global_load_lds_dwordx4 v[244:245], off
	s_waitcnt vmcnt(26)
	s_waitcnt lgkmcnt(0)
	s_barrier
	s_waitcnt lgkmcnt(0)
	v_mfma_f32_16x16x32_bf16 v[62:65], v[140:143], v[204:207], v[62:65]
	v_mfma_f32_16x16x32_bf16 v[58:61], v[180:183], v[204:207], v[58:61]
	v_mfma_f32_16x16x32_bf16 v[46:49], v[140:143], v[212:215], v[46:49]
	v_mfma_f32_16x16x32_bf16 v[42:45], v[180:183], v[212:215], v[42:45]
	v_mfma_f32_16x16x32_bf16 v[30:33], v[140:143], v[220:223], v[30:33]
	v_mfma_f32_16x16x32_bf16 v[26:29], v[180:183], v[220:223], v[26:29]
	v_mfma_f32_16x16x32_bf16 v[14:17], v[140:143], v[228:231], v[14:17]
	v_mfma_f32_16x16x32_bf16 v[10:13], v[180:183], v[228:231], v[10:13]
	v_mfma_f32_16x16x32_bf16 v[62:65], v[144:147], v[208:211], v[62:65]
	v_mfma_f32_16x16x32_bf16 v[58:61], v[184:187], v[208:211], v[58:61]
	v_mfma_f32_16x16x32_bf16 v[46:49], v[144:147], v[216:219], v[46:49]
	v_mfma_f32_16x16x32_bf16 v[42:45], v[184:187], v[216:219], v[42:45]
	v_mfma_f32_16x16x32_bf16 v[30:33], v[144:147], v[224:227], v[30:33]
	v_mfma_f32_16x16x32_bf16 v[26:29], v[184:187], v[224:227], v[26:29]
	v_mfma_f32_16x16x32_bf16 v[14:17], v[144:147], v[232:235], v[14:17]
	v_mfma_f32_16x16x32_bf16 v[10:13], v[184:187], v[232:235], v[10:13]
	v_mfma_f32_16x16x32_bf16 v[54:57], v[188:191], v[204:207], v[54:57]
	v_mfma_f32_16x16x32_bf16 v[50:53], v[196:199], v[204:207], v[50:53]
	v_mfma_f32_16x16x32_bf16 v[38:41], v[188:191], v[212:215], v[38:41]
	v_mfma_f32_16x16x32_bf16 v[34:37], v[196:199], v[212:215], v[34:37]
	v_mfma_f32_16x16x32_bf16 v[22:25], v[188:191], v[220:223], v[22:25]
	v_mfma_f32_16x16x32_bf16 v[18:21], v[196:199], v[220:223], v[18:21]
	v_mfma_f32_16x16x32_bf16 v[6:9], v[188:191], v[228:231], v[6:9]
	v_mfma_f32_16x16x32_bf16 v[2:5], v[196:199], v[228:231], v[2:5]
	v_mfma_f32_16x16x32_bf16 v[54:57], v[192:195], v[208:211], v[54:57]
	v_mfma_f32_16x16x32_bf16 v[50:53], v[200:203], v[208:211], v[50:53]
	v_mfma_f32_16x16x32_bf16 v[38:41], v[192:195], v[216:219], v[38:41]
	v_mfma_f32_16x16x32_bf16 v[34:37], v[200:203], v[216:219], v[34:37]
	v_mfma_f32_16x16x32_bf16 v[22:25], v[192:195], v[224:227], v[22:25]
	v_mfma_f32_16x16x32_bf16 v[18:21], v[200:203], v[224:227], v[18:21]
	v_mfma_f32_16x16x32_bf16 v[6:9], v[192:195], v[232:235], v[6:9]
	v_mfma_f32_16x16x32_bf16 v[2:5], v[200:203], v[232:235], v[2:5]
	s_barrier
	s_add_i32 s31, 0, 0x18000
	s_add_i32 s35, 0, 0x1c000
	v_add_u32_e32 v184, s31, v160
	v_add_u32_e32 v200, s35, v160
	ds_read_b128 v[140:143], v184
	ds_read_b128 v[144:147], v184 offset:1024
	ds_read_b128 v[180:183], v184 offset:2048
	ds_read_b128 v[184:187], v184 offset:3072
	ds_read_b128 v[188:191], v200
	ds_read_b128 v[192:195], v200 offset:1024
	ds_read_b128 v[196:199], v200 offset:2048
	ds_read_b128 v[200:203], v200 offset:3072
	s_add_u32 s10, s10, s16
	s_addc_u32 s11, s11, 0
	s_mov_b32 m0, s53
	v_lshl_add_u64 v[246:247], s[10:11], 0, v[130:131]
	ds_read_b128 v[204:207], v172 offset:32768
	ds_read_b128 v[208:211], v172 offset:33792
	ds_read_b128 v[212:215], v172 offset:34816
	ds_read_b128 v[216:219], v172 offset:35840
	ds_read_b128 v[220:223], v172 offset:36864
	ds_read_b128 v[224:227], v172 offset:37888
	ds_read_b128 v[228:231], v172 offset:38912
	ds_read_b128 v[232:235], v172 offset:39936
	global_load_lds_dwordx4 v[246:247], off
	v_lshl_add_u64 v[246:247], s[10:11], 0, v[132:133]
	s_mov_b32 m0, s54
	s_nop 0
	global_load_lds_dwordx4 v[246:247], off
	s_waitcnt vmcnt(8)
	s_waitcnt lgkmcnt(0)
	s_barrier
	s_waitcnt lgkmcnt(0)
	v_mfma_f32_16x16x32_bf16 v[126:129], v[140:143], v[204:207], v[126:129]
	v_mfma_f32_16x16x32_bf16 v[122:125], v[180:183], v[204:207], v[122:125]
	v_mfma_f32_16x16x32_bf16 v[110:113], v[140:143], v[212:215], v[110:113]
	v_mfma_f32_16x16x32_bf16 v[106:109], v[180:183], v[212:215], v[106:109]
	v_mfma_f32_16x16x32_bf16 v[94:97], v[140:143], v[220:223], v[94:97]
	v_mfma_f32_16x16x32_bf16 v[90:93], v[180:183], v[220:223], v[90:93]
	v_mfma_f32_16x16x32_bf16 v[78:81], v[140:143], v[228:231], v[78:81]
	v_mfma_f32_16x16x32_bf16 v[74:77], v[180:183], v[228:231], v[74:77]
	v_mfma_f32_16x16x32_bf16 v[126:129], v[144:147], v[208:211], v[126:129]
	v_mfma_f32_16x16x32_bf16 v[122:125], v[184:187], v[208:211], v[122:125]
	v_mfma_f32_16x16x32_bf16 v[110:113], v[144:147], v[216:219], v[110:113]
	v_mfma_f32_16x16x32_bf16 v[106:109], v[184:187], v[216:219], v[106:109]
	v_mfma_f32_16x16x32_bf16 v[94:97], v[144:147], v[224:227], v[94:97]
	v_mfma_f32_16x16x32_bf16 v[90:93], v[184:187], v[224:227], v[90:93]
	v_mfma_f32_16x16x32_bf16 v[78:81], v[144:147], v[232:235], v[78:81]
	v_mfma_f32_16x16x32_bf16 v[74:77], v[184:187], v[232:235], v[74:77]
	v_mfma_f32_16x16x32_bf16 v[118:121], v[188:191], v[204:207], v[118:121]
	v_mfma_f32_16x16x32_bf16 v[114:117], v[196:199], v[204:207], v[114:117]
	v_mfma_f32_16x16x32_bf16 v[102:105], v[188:191], v[212:215], v[102:105]
	v_mfma_f32_16x16x32_bf16 v[98:101], v[196:199], v[212:215], v[98:101]
	v_mfma_f32_16x16x32_bf16 v[86:89], v[188:191], v[220:223], v[86:89]
	v_mfma_f32_16x16x32_bf16 v[82:85], v[196:199], v[220:223], v[82:85]
	v_mfma_f32_16x16x32_bf16 v[70:73], v[188:191], v[228:231], v[70:73]
	v_mfma_f32_16x16x32_bf16 v[66:69], v[196:199], v[228:231], v[66:69]
	v_mfma_f32_16x16x32_bf16 v[118:121], v[192:195], v[208:211], v[118:121]
	v_mfma_f32_16x16x32_bf16 v[114:117], v[200:203], v[208:211], v[114:117]
	v_mfma_f32_16x16x32_bf16 v[102:105], v[192:195], v[216:219], v[102:105]
	v_mfma_f32_16x16x32_bf16 v[98:101], v[200:203], v[216:219], v[98:101]
	v_mfma_f32_16x16x32_bf16 v[86:89], v[192:195], v[224:227], v[86:89]
	v_mfma_f32_16x16x32_bf16 v[82:85], v[200:203], v[224:227], v[82:85]
	v_mfma_f32_16x16x32_bf16 v[70:73], v[192:195], v[232:235], v[70:73]
	v_mfma_f32_16x16x32_bf16 v[66:69], v[200:203], v[232:235], v[66:69]
	s_barrier
	s_add_i32 s10, s31, s20
	v_lshl_add_u64 v[148:149], v[148:149], 0, s[94:95]
	s_mov_b32 m0, s10
	ds_read_b128 v[204:207], v172 offset:49152
	ds_read_b128 v[208:211], v172 offset:50176
	ds_read_b128 v[212:215], v172 offset:51200
	ds_read_b128 v[216:219], v172 offset:52224
	ds_read_b128 v[220:223], v172 offset:53248
	ds_read_b128 v[224:227], v172 offset:54272
	ds_read_b128 v[228:231], v172 offset:55296
	ds_read_b128 v[232:235], v172 offset:56320
	global_load_lds_dwordx4 v[148:149], off
	v_lshl_add_u64 v[148:149], v[236:237], 0, s[94:95]
	s_add_i32 m0, s10, 0x2000
	s_add_i32 s10, s35, s20
	global_load_lds_dwordx4 v[148:149], off
	v_lshl_add_u64 v[148:149], v[238:239], 0, s[94:95]
	s_mov_b32 m0, s10
	s_nop 0
	global_load_lds_dwordx4 v[148:149], off
	v_lshl_add_u64 v[148:149], v[240:241], 0, s[94:95]
	s_add_i32 m0, s10, 0x2000
	s_nop 0
	global_load_lds_dwordx4 v[148:149], off
	v_lshl_add_u64 v[148:149], v[242:243], 0, s[94:95]
	s_mov_b32 m0, s56
	s_nop 0
	global_load_lds_dwordx4 v[148:149], off
	v_lshl_add_u64 v[148:149], v[244:245], 0, s[94:95]
	s_mov_b32 m0, s57
	s_nop 0
	global_load_lds_dwordx4 v[148:149], off
	s_waitcnt vmcnt(8)
	s_waitcnt lgkmcnt(0)
	s_barrier
	s_waitcnt lgkmcnt(0)
	v_mfma_f32_16x16x32_bf16 v[62:65], v[140:143], v[204:207], v[62:65]
	v_mfma_f32_16x16x32_bf16 v[58:61], v[180:183], v[204:207], v[58:61]
	v_mfma_f32_16x16x32_bf16 v[46:49], v[140:143], v[212:215], v[46:49]
	v_mfma_f32_16x16x32_bf16 v[42:45], v[180:183], v[212:215], v[42:45]
	v_mfma_f32_16x16x32_bf16 v[30:33], v[140:143], v[220:223], v[30:33]
	v_mfma_f32_16x16x32_bf16 v[26:29], v[180:183], v[220:223], v[26:29]
	v_mfma_f32_16x16x32_bf16 v[14:17], v[140:143], v[228:231], v[14:17]
	v_mfma_f32_16x16x32_bf16 v[10:13], v[180:183], v[228:231], v[10:13]
	v_mfma_f32_16x16x32_bf16 v[62:65], v[144:147], v[208:211], v[62:65]
	v_mfma_f32_16x16x32_bf16 v[58:61], v[184:187], v[208:211], v[58:61]
	v_mfma_f32_16x16x32_bf16 v[46:49], v[144:147], v[216:219], v[46:49]
	v_mfma_f32_16x16x32_bf16 v[42:45], v[184:187], v[216:219], v[42:45]
	v_mfma_f32_16x16x32_bf16 v[30:33], v[144:147], v[224:227], v[30:33]
	v_mfma_f32_16x16x32_bf16 v[26:29], v[184:187], v[224:227], v[26:29]
	v_mfma_f32_16x16x32_bf16 v[14:17], v[144:147], v[232:235], v[14:17]
	v_mfma_f32_16x16x32_bf16 v[10:13], v[184:187], v[232:235], v[10:13]
	v_mfma_f32_16x16x32_bf16 v[54:57], v[188:191], v[204:207], v[54:57]
	v_mfma_f32_16x16x32_bf16 v[50:53], v[196:199], v[204:207], v[50:53]
	v_mfma_f32_16x16x32_bf16 v[38:41], v[188:191], v[212:215], v[38:41]
	v_mfma_f32_16x16x32_bf16 v[34:37], v[196:199], v[212:215], v[34:37]
	v_mfma_f32_16x16x32_bf16 v[22:25], v[188:191], v[220:223], v[22:25]
	v_mfma_f32_16x16x32_bf16 v[18:21], v[196:199], v[220:223], v[18:21]
	v_mfma_f32_16x16x32_bf16 v[6:9], v[188:191], v[228:231], v[6:9]
	v_mfma_f32_16x16x32_bf16 v[2:5], v[196:199], v[228:231], v[2:5]
	v_mfma_f32_16x16x32_bf16 v[54:57], v[192:195], v[208:211], v[54:57]
	v_mfma_f32_16x16x32_bf16 v[50:53], v[200:203], v[208:211], v[50:53]
	v_mfma_f32_16x16x32_bf16 v[38:41], v[192:195], v[216:219], v[38:41]
	v_mfma_f32_16x16x32_bf16 v[34:37], v[200:203], v[216:219], v[34:37]
	v_mfma_f32_16x16x32_bf16 v[22:25], v[192:195], v[224:227], v[22:25]
	v_mfma_f32_16x16x32_bf16 v[18:21], v[200:203], v[224:227], v[18:21]
	v_mfma_f32_16x16x32_bf16 v[6:9], v[192:195], v[232:235], v[6:9]
	v_mfma_f32_16x16x32_bf16 v[2:5], v[200:203], v[232:235], v[2:5]
	s_barrier
	s_add_u32 s2, s2, 0x100
	s_addc_u32 s3, s3, 0
	s_add_u32 s19, s19, 0x100
	s_addc_u32 s29, s29, 0
	s_cmp_ge_u32 s30, s55
	s_mov_b32 s10, s30
	s_cbranch_scc0 .LBB0_360
	s_branch .Lkexit_360

.LBB0_397:
	s_and_b64 vcc, exec, s[8:9]
	s_mov_b64 s[2:3], -1
	s_cbranch_vccnz .LBB0_351
	s_mov_b32 s101, 1
	v_lshl_add_u32 v2, s64, 8, v162
	v_ashrrev_i32_e32 v3, 31, v2
	s_mov_b32 m0, s21
	v_lshl_add_u64 v[2:3], v[2:3], 4, s[98:99]
	s_mov_b64 s[2:3], 0x800
	global_load_lds_dwordx4 v[2:3], off
	v_lshl_add_u64 v[2:3], v[2:3], 0, s[2:3]
	s_add_i32 m0, s21, 0x400
	v_readlane_b32 s2, v248, 29
	global_load_lds_dwordx4 v[2:3], off
	v_readlane_b32 s3, v248, 30
	s_andn2_b64 vcc, exec, s[2:3]
	s_cbranch_vccnz .LBB0_350
	s_barrier
	s_branch .LBB0_350

.LBB0_408:
	s_add_i32 m0, s35, 0x18000
	v_lshl_add_u64 v[10:11], v[10:11], 0, s[94:95]
	s_waitcnt vmcnt(2)
	s_barrier
	global_load_lds_dwordx4 v[10:11], off
	v_lshl_add_u64 v[6:7], v[6:7], 0, s[94:95]
	s_add_i32 m0, s35, 0x1a000
	s_add_i32 s55, s35, 0x8000
	global_load_lds_dwordx4 v[6:7], off
	v_lshl_add_u64 v[6:7], v[8:9], 0, s[94:95]
	s_mov_b32 m0, s55
	s_add_i32 s56, s35, 0xa000
	global_load_lds_dwordx4 v[6:7], off
	v_lshl_add_u64 v[6:7], v[12:13], 0, s[94:95]
	s_mov_b32 m0, s56
	v_lshl_add_u64 v[4:5], v[4:5], 0, s[94:95]
	global_load_lds_dwordx4 v[6:7], off
	s_add_i32 m0, s35, 0x1c000
	v_lshl_add_u64 v[2:3], v[2:3], 0, s[94:95]
	global_load_lds_dwordx4 v[4:5], off
	s_add_i32 m0, s35, 0x1e000
	v_or_b32_e32 v142, s7, v21
	global_load_lds_dwordx4 v[2:3], off
	v_lshlrev_b32_e32 v3, 6, v142
	s_movk_i32 s7, 0x3c0
	v_lshlrev_b32_e32 v4, 2, v142
	v_lshlrev_b32_e32 v2, 3, v15
	v_and_or_b32 v3, v3, s7, v22
	v_and_b32_e32 v4, 32, v4
	v_lshlrev_b32_e32 v5, 2, v21
	v_bitop3_b32 v4, v3, s6, v4 bitop3:0xde
	v_lshl_or_b32 v3, v21, 6, v22
	s_lshl_b32 s6, s1, 12
	v_and_b32_e32 v5, 32, v5
	v_lshl_or_b32 v144, s1, 5, v2
	v_add_u32_e32 v2, v17, v14
	s_lshr_b32 s57, s15, 6
	v_bitop3_b32 v143, v3, s6, v5 bitop3:0xde
	v_add_lshl_u32 v2, v2, v16, 1
	v_mov_b32_e32 v2, v246
	v_mov_b32_e32 v3, v1
	s_waitcnt vmcnt(6)
	s_add_i32 s58, s57, -2
	v_lshl_add_u64 v[136:137], s[80:81], 0, v[2:3]
	v_add_u32_e32 v2, v20, v18
	s_cmpk_lt_u32 s0, 0x100
	v_lshlrev_b32_e32 v5, 4, v21
	v_add_lshl_u32 v2, v2, v19, 1
	v_mov_b32_e32 v2, v247
	v_or_b32_e32 v145, v142, v22
	s_cselect_b64 s[10:11], -1, 0
	s_mov_b32 s13, s81
	v_lshl_add_u64 v[138:139], s[80:81], 0, v[2:3]
	s_mov_b32 s59, 0
	v_add_u32_e32 v146, 0, v4
	v_lshrrev_b32_e32 v245, 10, v146
	v_lshl_or_b32 v146, v245, 10, v243
	v_add_u32_e32 v147, s31, v5
	s_barrier
	s_mov_b32 s101, 0
	s_branch .LBB0_411

.LBB0_418:
	s_add_u32 s16, s16, 0x80
	s_addc_u32 s17, s17, 0
	s_add_u32 s64, s20, 0x100
	v_mov_b32_e32 v2, 0
	s_addc_u32 s65, s21, 0
	s_mov_b32 s20, 0
	v_mov_b32_e32 v3, v2
	v_mov_b32_e32 v4, v2
	v_mov_b32_e32 v5, v2
	v_mov_b32_e32 v6, v2
	v_mov_b32_e32 v7, v2
	v_mov_b32_e32 v8, v2
	v_mov_b32_e32 v9, v2
	v_mov_b32_e32 v18, v2
	v_mov_b32_e32 v19, v2
	v_mov_b32_e32 v20, v2
	v_mov_b32_e32 v21, v2
	v_mov_b32_e32 v22, v2
	v_mov_b32_e32 v23, v2
	v_mov_b32_e32 v24, v2
	v_mov_b32_e32 v25, v2
	v_mov_b32_e32 v34, v2
	v_mov_b32_e32 v35, v2
	v_mov_b32_e32 v36, v2
	v_mov_b32_e32 v37, v2
	v_mov_b32_e32 v38, v2
	v_mov_b32_e32 v39, v2
	v_mov_b32_e32 v40, v2
	v_mov_b32_e32 v41, v2
	v_mov_b32_e32 v50, v2
	v_mov_b32_e32 v51, v2
	v_mov_b32_e32 v52, v2
	v_mov_b32_e32 v53, v2
	v_mov_b32_e32 v54, v2
	v_mov_b32_e32 v55, v2
	v_mov_b32_e32 v56, v2
	v_mov_b32_e32 v57, v2
	v_mov_b32_e32 v10, v2
	v_mov_b32_e32 v11, v2
	v_mov_b32_e32 v12, v2
	v_mov_b32_e32 v13, v2
	v_mov_b32_e32 v14, v2
	v_mov_b32_e32 v15, v2
	v_mov_b32_e32 v16, v2
	v_mov_b32_e32 v17, v2
	v_mov_b32_e32 v26, v2
	v_mov_b32_e32 v27, v2
	v_mov_b32_e32 v28, v2
	v_mov_b32_e32 v29, v2
	v_mov_b32_e32 v30, v2
	v_mov_b32_e32 v31, v2
	v_mov_b32_e32 v32, v2
	v_mov_b32_e32 v33, v2
	v_mov_b32_e32 v42, v2
	v_mov_b32_e32 v43, v2
	v_mov_b32_e32 v44, v2
	v_mov_b32_e32 v45, v2
	v_mov_b32_e32 v46, v2
	v_mov_b32_e32 v47, v2
	v_mov_b32_e32 v48, v2
	v_mov_b32_e32 v49, v2
	v_mov_b32_e32 v58, v2
	v_mov_b32_e32 v59, v2
	v_mov_b32_e32 v60, v2
	v_mov_b32_e32 v61, v2
	v_mov_b32_e32 v62, v2
	v_mov_b32_e32 v63, v2
	v_mov_b32_e32 v64, v2
	v_mov_b32_e32 v65, v2
	v_mov_b32_e32 v66, v2
	v_mov_b32_e32 v67, v2
	v_mov_b32_e32 v68, v2
	v_mov_b32_e32 v69, v2
	v_mov_b32_e32 v70, v2
	v_mov_b32_e32 v71, v2
	v_mov_b32_e32 v72, v2
	v_mov_b32_e32 v73, v2
	v_mov_b32_e32 v82, v2
	v_mov_b32_e32 v83, v2
	v_mov_b32_e32 v84, v2
	v_mov_b32_e32 v85, v2
	v_mov_b32_e32 v86, v2
	v_mov_b32_e32 v87, v2
	v_mov_b32_e32 v88, v2
	v_mov_b32_e32 v89, v2
	v_mov_b32_e32 v98, v2
	v_mov_b32_e32 v99, v2
	v_mov_b32_e32 v100, v2
	v_mov_b32_e32 v101, v2
	v_mov_b32_e32 v102, v2
	v_mov_b32_e32 v103, v2
	v_mov_b32_e32 v104, v2
	v_mov_b32_e32 v105, v2
	v_mov_b32_e32 v114, v2
	v_mov_b32_e32 v115, v2
	v_mov_b32_e32 v116, v2
	v_mov_b32_e32 v117, v2
	v_mov_b32_e32 v118, v2
	v_mov_b32_e32 v119, v2
	v_mov_b32_e32 v120, v2
	v_mov_b32_e32 v121, v2
	v_mov_b32_e32 v74, v2
	v_mov_b32_e32 v75, v2
	v_mov_b32_e32 v76, v2
	v_mov_b32_e32 v77, v2
	v_mov_b32_e32 v78, v2
	v_mov_b32_e32 v79, v2
	v_mov_b32_e32 v80, v2
	v_mov_b32_e32 v81, v2
	v_mov_b32_e32 v90, v2
	v_mov_b32_e32 v91, v2
	v_mov_b32_e32 v92, v2
	v_mov_b32_e32 v93, v2
	v_mov_b32_e32 v94, v2
	v_mov_b32_e32 v95, v2
	v_mov_b32_e32 v96, v2
	v_mov_b32_e32 v97, v2
	v_mov_b32_e32 v106, v2
	v_mov_b32_e32 v107, v2
	v_mov_b32_e32 v108, v2
	v_mov_b32_e32 v109, v2
	v_mov_b32_e32 v110, v2
	v_mov_b32_e32 v111, v2
	v_mov_b32_e32 v112, v2
	v_mov_b32_e32 v113, v2
	v_mov_b32_e32 v122, v2
	v_mov_b32_e32 v123, v2
	v_mov_b32_e32 v124, v2
	v_mov_b32_e32 v125, v2
	v_mov_b32_e32 v126, v2
	v_mov_b32_e32 v127, v2
	v_mov_b32_e32 v128, v2
	v_mov_b32_e32 v129, v2
	s_cmp_eq_u32 s101, 0
	s_cbranch_scc1 .LBB0_419
	s_add_i32 s66, s20, 2
	s_add_u32 s67, s16, 0x80
	s_addc_u32 s21, s17, 0
	s_add_i32 s72, 0, 0x10000
	s_cmp_eq_u32 s58, s20
	s_cselect_b32 s21, s1, s21
	s_cselect_b32 s20, s0, s67
	v_add_u32_e32 v140, s72, v143
	s_cselect_b32 s71, s15, s65
	s_cselect_b32 s70, s14, s64
	s_add_i32 s67, 0, 0x14000
	ds_read_b128 v[160:163], v140
	ds_read_b128 v[164:167], v140 offset:1024
	ds_read_b128 v[168:171], v140 offset:2048
	ds_read_b128 v[172:175], v140 offset:3072
	v_add_u32_e32 v140, s67, v143
	ds_read_b128 v[176:179], v140
	ds_read_b128 v[180:183], v140 offset:1024
	ds_read_b128 v[184:187], v140 offset:2048
	ds_read_b128 v[188:191], v140 offset:3072
	v_lshl_add_u64 v[140:141], s[16:17], 0, v[136:137]
	s_add_i32 m0, s35, 0xc000
	ds_read_b128 v[192:195], v146
	ds_read_b128 v[196:199], v146 offset:1024
	ds_read_b128 v[200:203], v146 offset:2048
	ds_read_b128 v[204:207], v146 offset:3072
	ds_read_b128 v[208:211], v146 offset:4096
	ds_read_b128 v[212:215], v146 offset:5120
	ds_read_b128 v[216:219], v146 offset:6144
	ds_read_b128 v[220:223], v146 offset:7168
	global_load_lds_dwordx4 v[140:141], off
	v_lshl_add_u64 v[140:141], s[16:17], 0, v[138:139]
	s_add_i32 m0, s35, 0xe000
	s_nop 0
	global_load_lds_dwordx4 v[140:141], off
	s_waitcnt vmcnt(26)
	s_waitcnt lgkmcnt(0)
	s_barrier
	s_waitcnt lgkmcnt(0)
	v_mfma_f32_16x16x32_bf16 v[126:129], v[160:163], v[192:195], v[126:129]
	v_mfma_f32_16x16x32_bf16 v[122:125], v[168:171], v[192:195], v[122:125]
	v_mfma_f32_16x16x32_bf16 v[110:113], v[160:163], v[200:203], v[110:113]
	v_mfma_f32_16x16x32_bf16 v[106:109], v[168:171], v[200:203], v[106:109]
	v_mfma_f32_16x16x32_bf16 v[94:97], v[160:163], v[208:211], v[94:97]
	v_mfma_f32_16x16x32_bf16 v[90:93], v[168:171], v[208:211], v[90:93]
	v_mfma_f32_16x16x32_bf16 v[78:81], v[160:163], v[216:219], v[78:81]
	v_mfma_f32_16x16x32_bf16 v[74:77], v[168:171], v[216:219], v[74:77]
	v_mfma_f32_16x16x32_bf16 v[126:129], v[164:167], v[196:199], v[126:129]
	v_mfma_f32_16x16x32_bf16 v[122:125], v[172:175], v[196:199], v[122:125]
	v_mfma_f32_16x16x32_bf16 v[110:113], v[164:167], v[204:207], v[110:113]
	v_mfma_f32_16x16x32_bf16 v[106:109], v[172:175], v[204:207], v[106:109]
	v_mfma_f32_16x16x32_bf16 v[94:97], v[164:167], v[212:215], v[94:97]
	v_mfma_f32_16x16x32_bf16 v[90:93], v[172:175], v[212:215], v[90:93]
	v_mfma_f32_16x16x32_bf16 v[78:81], v[164:167], v[220:223], v[78:81]
	v_mfma_f32_16x16x32_bf16 v[74:77], v[172:175], v[220:223], v[74:77]
	v_mfma_f32_16x16x32_bf16 v[118:121], v[176:179], v[192:195], v[118:121]
	v_mfma_f32_16x16x32_bf16 v[114:117], v[184:187], v[192:195], v[114:117]
	v_mfma_f32_16x16x32_bf16 v[102:105], v[176:179], v[200:203], v[102:105]
	v_mfma_f32_16x16x32_bf16 v[98:101], v[184:187], v[200:203], v[98:101]
	v_mfma_f32_16x16x32_bf16 v[86:89], v[176:179], v[208:211], v[86:89]
	v_mfma_f32_16x16x32_bf16 v[82:85], v[184:187], v[208:211], v[82:85]
	v_mfma_f32_16x16x32_bf16 v[70:73], v[176:179], v[216:219], v[70:73]
	v_mfma_f32_16x16x32_bf16 v[66:69], v[184:187], v[216:219], v[66:69]
	v_mfma_f32_16x16x32_bf16 v[118:121], v[180:183], v[196:199], v[118:121]
	v_mfma_f32_16x16x32_bf16 v[114:117], v[188:191], v[196:199], v[114:117]
	v_mfma_f32_16x16x32_bf16 v[102:105], v[180:183], v[204:207], v[102:105]
	v_mfma_f32_16x16x32_bf16 v[98:101], v[188:191], v[204:207], v[98:101]
	v_mfma_f32_16x16x32_bf16 v[86:89], v[180:183], v[212:215], v[86:89]
	v_mfma_f32_16x16x32_bf16 v[82:85], v[188:191], v[212:215], v[82:85]
	v_mfma_f32_16x16x32_bf16 v[70:73], v[180:183], v[220:223], v[70:73]
	v_mfma_f32_16x16x32_bf16 v[66:69], v[188:191], v[220:223], v[66:69]
	s_barrier
	s_add_i32 s72, s72, s30
	v_lshl_add_u64 v[140:141], s[70:71], 0, v[0:1]
	s_mov_b32 m0, s72
	ds_read_b128 v[192:195], v146 offset:16384
	ds_read_b128 v[196:199], v146 offset:17408
	ds_read_b128 v[200:203], v146 offset:18432
	ds_read_b128 v[204:207], v146 offset:19456
	ds_read_b128 v[208:211], v146 offset:20480
	ds_read_b128 v[212:215], v146 offset:21504
	ds_read_b128 v[216:219], v146 offset:22528
	ds_read_b128 v[220:223], v146 offset:23552
	global_load_lds_dwordx4 v[140:141], off
	s_add_i32 m0, s72, 0x2000
	v_lshl_add_u64 v[148:149], s[70:71], 0, v[134:135]
	s_add_u32 s70, s70, s80
	s_addc_u32 s71, s71, 0
	s_add_i32 s67, s67, s30
	global_load_lds_dwordx4 v[148:149], off
	v_lshl_add_u64 v[224:225], s[70:71], 0, v[0:1]
	s_mov_b32 m0, s67
	v_lshl_add_u64 v[226:227], s[70:71], 0, v[134:135]
	global_load_lds_dwordx4 v[224:225], off
	s_add_i32 m0, s67, 0x2000
	v_lshl_add_u64 v[228:229], s[20:21], 0, v[130:131]
	global_load_lds_dwordx4 v[226:227], off
	s_mov_b32 m0, s35
	v_lshl_add_u64 v[230:231], s[20:21], 0, v[132:133]
	global_load_lds_dwordx4 v[228:229], off
	s_mov_b32 m0, s52
	s_nop 0
	global_load_lds_dwordx4 v[230:231], off
	s_waitcnt vmcnt(26)
	s_waitcnt lgkmcnt(0)
	s_barrier
	s_waitcnt lgkmcnt(0)
	v_mfma_f32_16x16x32_bf16 v[62:65], v[160:163], v[192:195], v[62:65]
	v_mfma_f32_16x16x32_bf16 v[58:61], v[168:171], v[192:195], v[58:61]
	v_mfma_f32_16x16x32_bf16 v[46:49], v[160:163], v[200:203], v[46:49]
	v_mfma_f32_16x16x32_bf16 v[42:45], v[168:171], v[200:203], v[42:45]
	v_mfma_f32_16x16x32_bf16 v[30:33], v[160:163], v[208:211], v[30:33]
	v_mfma_f32_16x16x32_bf16 v[26:29], v[168:171], v[208:211], v[26:29]
	v_mfma_f32_16x16x32_bf16 v[14:17], v[160:163], v[216:219], v[14:17]
	v_mfma_f32_16x16x32_bf16 v[10:13], v[168:171], v[216:219], v[10:13]
	v_mfma_f32_16x16x32_bf16 v[62:65], v[164:167], v[196:199], v[62:65]
	v_mfma_f32_16x16x32_bf16 v[58:61], v[172:175], v[196:199], v[58:61]
	v_mfma_f32_16x16x32_bf16 v[46:49], v[164:167], v[204:207], v[46:49]
	v_mfma_f32_16x16x32_bf16 v[42:45], v[172:175], v[204:207], v[42:45]
	v_mfma_f32_16x16x32_bf16 v[30:33], v[164:167], v[212:215], v[30:33]
	v_mfma_f32_16x16x32_bf16 v[26:29], v[172:175], v[212:215], v[26:29]
	v_mfma_f32_16x16x32_bf16 v[14:17], v[164:167], v[220:223], v[14:17]
	v_mfma_f32_16x16x32_bf16 v[10:13], v[172:175], v[220:223], v[10:13]
	v_mfma_f32_16x16x32_bf16 v[54:57], v[176:179], v[192:195], v[54:57]
	v_mfma_f32_16x16x32_bf16 v[50:53], v[184:187], v[192:195], v[50:53]
	v_mfma_f32_16x16x32_bf16 v[38:41], v[176:179], v[200:203], v[38:41]
	v_mfma_f32_16x16x32_bf16 v[34:37], v[184:187], v[200:203], v[34:37]
	v_mfma_f32_16x16x32_bf16 v[22:25], v[176:179], v[208:211], v[22:25]
	v_mfma_f32_16x16x32_bf16 v[18:21], v[184:187], v[208:211], v[18:21]
	v_mfma_f32_16x16x32_bf16 v[6:9], v[176:179], v[216:219], v[6:9]
	v_mfma_f32_16x16x32_bf16 v[2:5], v[184:187], v[216:219], v[2:5]
	v_mfma_f32_16x16x32_bf16 v[54:57], v[180:183], v[196:199], v[54:57]
	v_mfma_f32_16x16x32_bf16 v[50:53], v[188:191], v[196:199], v[50:53]
	v_mfma_f32_16x16x32_bf16 v[38:41], v[180:183], v[204:207], v[38:41]
	v_mfma_f32_16x16x32_bf16 v[34:37], v[188:191], v[204:207], v[34:37]
	v_mfma_f32_16x16x32_bf16 v[22:25], v[180:183], v[212:215], v[22:25]
	v_mfma_f32_16x16x32_bf16 v[18:21], v[188:191], v[212:215], v[18:21]
	v_mfma_f32_16x16x32_bf16 v[6:9], v[180:183], v[220:223], v[6:9]
	v_mfma_f32_16x16x32_bf16 v[2:5], v[188:191], v[220:223], v[2:5]
	s_barrier
	s_add_i32 s67, 0, 0x18000
	v_add_u32_e32 v159, s67, v143
	s_add_i32 s70, 0, 0x1c000
	ds_read_b128 v[160:163], v159
	ds_read_b128 v[164:167], v159 offset:1024
	ds_read_b128 v[168:171], v159 offset:2048
	ds_read_b128 v[172:175], v159 offset:3072
	v_add_u32_e32 v159, s70, v143
	ds_read_b128 v[176:179], v159
	ds_read_b128 v[180:183], v159 offset:1024
	ds_read_b128 v[184:187], v159 offset:2048
	ds_read_b128 v[188:191], v159 offset:3072
	s_add_u32 s20, s20, s80
	s_addc_u32 s21, s21, 0
	s_mov_b32 m0, s53
	v_lshl_add_u64 v[232:233], s[20:21], 0, v[130:131]
	ds_read_b128 v[192:195], v146 offset:32768
	ds_read_b128 v[196:199], v146 offset:33792
	ds_read_b128 v[200:203], v146 offset:34816
	ds_read_b128 v[204:207], v146 offset:35840
	ds_read_b128 v[208:211], v146 offset:36864
	ds_read_b128 v[212:215], v146 offset:37888
	ds_read_b128 v[216:219], v146 offset:38912
	ds_read_b128 v[220:223], v146 offset:39936
	global_load_lds_dwordx4 v[232:233], off
	v_lshl_add_u64 v[232:233], s[20:21], 0, v[132:133]
	s_mov_b32 m0, s54
	s_nop 0
	global_load_lds_dwordx4 v[232:233], off
	s_waitcnt vmcnt(8)
	s_waitcnt lgkmcnt(0)
	s_barrier
	s_waitcnt lgkmcnt(0)
	v_mfma_f32_16x16x32_bf16 v[126:129], v[160:163], v[192:195], v[126:129]
	v_mfma_f32_16x16x32_bf16 v[122:125], v[168:171], v[192:195], v[122:125]
	v_mfma_f32_16x16x32_bf16 v[110:113], v[160:163], v[200:203], v[110:113]
	v_mfma_f32_16x16x32_bf16 v[106:109], v[168:171], v[200:203], v[106:109]
	v_mfma_f32_16x16x32_bf16 v[94:97], v[160:163], v[208:211], v[94:97]
	v_mfma_f32_16x16x32_bf16 v[90:93], v[168:171], v[208:211], v[90:93]
	v_mfma_f32_16x16x32_bf16 v[78:81], v[160:163], v[216:219], v[78:81]
	v_mfma_f32_16x16x32_bf16 v[74:77], v[168:171], v[216:219], v[74:77]
	v_mfma_f32_16x16x32_bf16 v[126:129], v[164:167], v[196:199], v[126:129]
	v_mfma_f32_16x16x32_bf16 v[122:125], v[172:175], v[196:199], v[122:125]
	v_mfma_f32_16x16x32_bf16 v[110:113], v[164:167], v[204:207], v[110:113]
	v_mfma_f32_16x16x32_bf16 v[106:109], v[172:175], v[204:207], v[106:109]
	v_mfma_f32_16x16x32_bf16 v[94:97], v[164:167], v[212:215], v[94:97]
	v_mfma_f32_16x16x32_bf16 v[90:93], v[172:175], v[212:215], v[90:93]
	v_mfma_f32_16x16x32_bf16 v[78:81], v[164:167], v[220:223], v[78:81]
	v_mfma_f32_16x16x32_bf16 v[74:77], v[172:175], v[220:223], v[74:77]
	v_mfma_f32_16x16x32_bf16 v[118:121], v[176:179], v[192:195], v[118:121]
	v_mfma_f32_16x16x32_bf16 v[114:117], v[184:187], v[192:195], v[114:117]
	v_mfma_f32_16x16x32_bf16 v[102:105], v[176:179], v[200:203], v[102:105]
	v_mfma_f32_16x16x32_bf16 v[98:101], v[184:187], v[200:203], v[98:101]
	v_mfma_f32_16x16x32_bf16 v[86:89], v[176:179], v[208:211], v[86:89]
	v_mfma_f32_16x16x32_bf16 v[82:85], v[184:187], v[208:211], v[82:85]
	v_mfma_f32_16x16x32_bf16 v[70:73], v[176:179], v[216:219], v[70:73]
	v_mfma_f32_16x16x32_bf16 v[66:69], v[184:187], v[216:219], v[66:69]
	v_mfma_f32_16x16x32_bf16 v[118:121], v[180:183], v[196:199], v[118:121]
	v_mfma_f32_16x16x32_bf16 v[114:117], v[188:191], v[196:199], v[114:117]
	v_mfma_f32_16x16x32_bf16 v[102:105], v[180:183], v[204:207], v[102:105]
	v_mfma_f32_16x16x32_bf16 v[98:101], v[188:191], v[204:207], v[98:101]
	v_mfma_f32_16x16x32_bf16 v[86:89], v[180:183], v[212:215], v[86:89]
	v_mfma_f32_16x16x32_bf16 v[82:85], v[188:191], v[212:215], v[82:85]
	v_mfma_f32_16x16x32_bf16 v[70:73], v[180:183], v[220:223], v[70:73]
	v_mfma_f32_16x16x32_bf16 v[66:69], v[188:191], v[220:223], v[66:69]
	s_barrier
	s_add_i32 s20, s67, s30
	v_lshl_add_u64 v[140:141], v[140:141], 0, s[94:95]
	s_mov_b32 m0, s20
	ds_read_b128 v[192:195], v146 offset:49152
	ds_read_b128 v[196:199], v146 offset:50176
	ds_read_b128 v[200:203], v146 offset:51200
	ds_read_b128 v[204:207], v146 offset:52224
	ds_read_b128 v[208:211], v146 offset:53248
	ds_read_b128 v[212:215], v146 offset:54272
	ds_read_b128 v[216:219], v146 offset:55296
	ds_read_b128 v[220:223], v146 offset:56320
	global_load_lds_dwordx4 v[140:141], off
	v_lshl_add_u64 v[140:141], v[148:149], 0, s[94:95]
	s_add_i32 m0, s20, 0x2000
	s_add_i32 s20, s70, s30
	global_load_lds_dwordx4 v[140:141], off
	v_lshl_add_u64 v[140:141], v[224:225], 0, s[94:95]
	s_mov_b32 m0, s20
	s_nop 0
	global_load_lds_dwordx4 v[140:141], off
	v_lshl_add_u64 v[140:141], v[226:227], 0, s[94:95]
	s_add_i32 m0, s20, 0x2000
	s_nop 0
	global_load_lds_dwordx4 v[140:141], off
	v_lshl_add_u64 v[140:141], v[228:229], 0, s[94:95]
	s_mov_b32 m0, s55
	s_nop 0
	global_load_lds_dwordx4 v[140:141], off
	v_lshl_add_u64 v[140:141], v[230:231], 0, s[94:95]
	s_mov_b32 m0, s56
	s_nop 0
	global_load_lds_dwordx4 v[140:141], off
	s_waitcnt vmcnt(8)
	s_waitcnt lgkmcnt(0)
	s_barrier
	s_waitcnt lgkmcnt(0)
	v_mfma_f32_16x16x32_bf16 v[62:65], v[160:163], v[192:195], v[62:65]
	v_mfma_f32_16x16x32_bf16 v[58:61], v[168:171], v[192:195], v[58:61]
	v_mfma_f32_16x16x32_bf16 v[46:49], v[160:163], v[200:203], v[46:49]
	v_mfma_f32_16x16x32_bf16 v[42:45], v[168:171], v[200:203], v[42:45]
	v_mfma_f32_16x16x32_bf16 v[30:33], v[160:163], v[208:211], v[30:33]
	v_mfma_f32_16x16x32_bf16 v[26:29], v[168:171], v[208:211], v[26:29]
	v_mfma_f32_16x16x32_bf16 v[14:17], v[160:163], v[216:219], v[14:17]
	v_mfma_f32_16x16x32_bf16 v[10:13], v[168:171], v[216:219], v[10:13]
	v_mfma_f32_16x16x32_bf16 v[62:65], v[164:167], v[196:199], v[62:65]
	v_mfma_f32_16x16x32_bf16 v[58:61], v[172:175], v[196:199], v[58:61]
	v_mfma_f32_16x16x32_bf16 v[46:49], v[164:167], v[204:207], v[46:49]
	v_mfma_f32_16x16x32_bf16 v[42:45], v[172:175], v[204:207], v[42:45]
	v_mfma_f32_16x16x32_bf16 v[30:33], v[164:167], v[212:215], v[30:33]
	v_mfma_f32_16x16x32_bf16 v[26:29], v[172:175], v[212:215], v[26:29]
	v_mfma_f32_16x16x32_bf16 v[14:17], v[164:167], v[220:223], v[14:17]
	v_mfma_f32_16x16x32_bf16 v[10:13], v[172:175], v[220:223], v[10:13]
	v_mfma_f32_16x16x32_bf16 v[54:57], v[176:179], v[192:195], v[54:57]
	v_mfma_f32_16x16x32_bf16 v[50:53], v[184:187], v[192:195], v[50:53]
	v_mfma_f32_16x16x32_bf16 v[38:41], v[176:179], v[200:203], v[38:41]
	v_mfma_f32_16x16x32_bf16 v[34:37], v[184:187], v[200:203], v[34:37]
	v_mfma_f32_16x16x32_bf16 v[22:25], v[176:179], v[208:211], v[22:25]
	v_mfma_f32_16x16x32_bf16 v[18:21], v[184:187], v[208:211], v[18:21]
	v_mfma_f32_16x16x32_bf16 v[6:9], v[176:179], v[216:219], v[6:9]
	v_mfma_f32_16x16x32_bf16 v[2:5], v[184:187], v[216:219], v[2:5]
	v_mfma_f32_16x16x32_bf16 v[54:57], v[180:183], v[196:199], v[54:57]
	v_mfma_f32_16x16x32_bf16 v[50:53], v[188:191], v[196:199], v[50:53]
	v_mfma_f32_16x16x32_bf16 v[38:41], v[180:183], v[204:207], v[38:41]
	v_mfma_f32_16x16x32_bf16 v[34:37], v[188:191], v[204:207], v[34:37]
	v_mfma_f32_16x16x32_bf16 v[22:25], v[180:183], v[212:215], v[22:25]
	v_mfma_f32_16x16x32_bf16 v[18:21], v[188:191], v[212:215], v[18:21]
	v_mfma_f32_16x16x32_bf16 v[6:9], v[180:183], v[220:223], v[6:9]
	v_mfma_f32_16x16x32_bf16 v[2:5], v[188:191], v[220:223], v[2:5]
	s_barrier
	s_add_u32 s16, s16, 0x100
	s_addc_u32 s17, s17, 0
	s_add_u32 s64, s64, 0x100
	s_addc_u32 s65, s65, 0
	s_cmp_ge_u32 s66, s57
	s_mov_b32 s20, s66
	s_cbranch_scc0 .LBB0_419
	s_branch .Lkexit_419

.LBB0_422:
	s_mov_b32 s100, 0xf3cf
	s_lshr_b32 s100, s100, s63
	s_bitcmp1_b32 s100, 0
	s_cselect_b64 vcc, -1, 0
	v_and_b32_e32 v234, 15, v150
	v_bfe_u32 v235, v150, 4, 2
	v_lshrrev_b32_e32 v236, 2, v234
	v_and_b32_e32 v234, 3, v234
	v_lshl_or_b32 v235, v236, 2, v235
	v_lshlrev_b32_e32 v234, 3, v234
	v_and_or_b32 v232, v142, -16, v235
	v_lshrrev_b32_e32 v233, 5, v144
	v_lshl_or_b32 v233, v233, 5, v234
	v_cndmask_b32_e32 v232, v142, v232, vcc
	v_cndmask_b32_e32 v233, v144, v233, vcc
	ds_read_b128 v[160:163], v147
	v_lshl_add_u32 v148, s62, 8, v232
	v_ashrrev_i32_e32 v149, 31, v148
	v_mul_lo_u32 v149, s68, v149
	v_mul_lo_u32 v159, s69, v148
	s_waitcnt lgkmcnt(0)
	v_mov_b32_e32 v166, v161
	v_mov_b32_e32 v167, v162
	v_mov_b32_e32 v161, v163
	v_mad_u64_u32 v[164:165], s[16:17], s68, v148, 0
	v_pk_add_f32 v[160:161], v[166:167], v[160:161]
	v_add3_u32 v165, v165, v149, v159
	v_add_f32_e32 v159, v160, v161
	v_fmamk_f32 v159, v159, 0x3a800000, v155
	v_rsq_f32_e32 v160, v159
	v_lshl_or_b32 v140, s63, 8, v233
	v_ashrrev_i32_e32 v141, 31, v140
	v_lshl_add_u64 v[162:163], v[164:165], 1, s[78:79]
	v_lshlrev_b64 v[140:141], 1, v[140:141]
	v_lshl_add_u64 v[162:163], v[162:163], 0, v[140:141]
	v_pk_mul_f32 v[128:129], v[128:129], v[160:161] op_sel_hi:[1,0]
	v_pk_mul_f32 v[126:127], v[126:127], v[160:161] op_sel_hi:[1,0]
	v_pk_mul_f32 v[164:165], v[124:125], v[160:161] op_sel_hi:[1,0]
	v_pk_mul_f32 v[124:125], v[122:123], v[160:161] op_sel_hi:[1,0]
	v_cvt_pk_bf16_f32 v122, v126, v127
	v_cvt_pk_bf16_f32 v123, v128, v129
	v_pk_mul_f32 v[120:121], v[120:121], v[160:161] op_sel_hi:[1,0]
	v_cvt_pk_bf16_f32 v124, v124, v125
	v_cvt_pk_bf16_f32 v125, v164, v165
	global_store_dwordx4 v[162:163], v[122:125], off
	v_pk_mul_f32 v[118:119], v[118:119], v[160:161] op_sel_hi:[1,0]
	s_and_b64 vcc, exec, s[6:7]
	v_pk_mul_f32 v[122:123], v[116:117], v[160:161] op_sel_hi:[1,0]
	v_pk_mul_f32 v[116:117], v[114:115], v[160:161] op_sel_hi:[1,0]
	v_cvt_pk_bf16_f32 v114, v118, v119
	v_cvt_pk_bf16_f32 v115, v120, v121
	v_or_b32_e32 v118, 16, v148
	v_cvt_pk_bf16_f32 v116, v116, v117
	v_cvt_pk_bf16_f32 v117, v122, v123
	global_store_dwordx4 v[162:163], v[114:117], off offset:256
	ds_read_b128 v[114:117], v147 offset:256
	v_mul_lo_u32 v122, s69, v118
	v_mad_u64_u32 v[118:119], s[16:17], s68, v118, 0
	v_add3_u32 v119, v119, v149, v122
	s_waitcnt lgkmcnt(0)
	v_mov_b32_e32 v120, v115
	v_mov_b32_e32 v121, v116
	v_mov_b32_e32 v115, v117
	v_pk_add_f32 v[114:115], v[120:121], v[114:115]
	v_lshl_add_u64 v[116:117], v[118:119], 1, s[78:79]
	v_add_f32_e32 v114, v114, v115
	v_fmamk_f32 v114, v114, 0x3a800000, v155
	v_rsq_f32_e32 v114, v114
	v_lshl_add_u64 v[116:117], v[116:117], 0, v[140:141]
	s_mov_b64 s[6:7], -1
	v_pk_mul_f32 v[112:113], v[112:113], v[114:115] op_sel_hi:[1,0]
	v_pk_mul_f32 v[110:111], v[110:111], v[114:115] op_sel_hi:[1,0]
	v_pk_mul_f32 v[118:119], v[108:109], v[114:115] op_sel_hi:[1,0]
	v_pk_mul_f32 v[108:109], v[106:107], v[114:115] op_sel_hi:[1,0]
	v_cvt_pk_bf16_f32 v106, v110, v111
	v_cvt_pk_bf16_f32 v107, v112, v113
	v_pk_mul_f32 v[104:105], v[104:105], v[114:115] op_sel_hi:[1,0]
	v_cvt_pk_bf16_f32 v108, v108, v109
	v_cvt_pk_bf16_f32 v109, v118, v119
	global_store_dwordx4 v[116:117], v[106:109], off
	v_pk_mul_f32 v[102:103], v[102:103], v[114:115] op_sel_hi:[1,0]
	s_nop 0
	v_pk_mul_f32 v[106:107], v[100:101], v[114:115] op_sel_hi:[1,0]
	v_pk_mul_f32 v[100:101], v[98:99], v[114:115] op_sel_hi:[1,0]
	v_cvt_pk_bf16_f32 v98, v102, v103
	v_cvt_pk_bf16_f32 v99, v104, v105
	v_or_b32_e32 v102, 32, v148
	v_cvt_pk_bf16_f32 v100, v100, v101
	v_cvt_pk_bf16_f32 v101, v106, v107
	global_store_dwordx4 v[116:117], v[98:101], off offset:256
	ds_read_b128 v[98:101], v147 offset:512
	v_mul_lo_u32 v106, s69, v102
	v_mad_u64_u32 v[102:103], s[16:17], s68, v102, 0
	v_add3_u32 v103, v103, v149, v106
	s_waitcnt lgkmcnt(0)
	v_mov_b32_e32 v104, v99
	v_mov_b32_e32 v105, v100
	v_mov_b32_e32 v99, v101
	v_pk_add_f32 v[98:99], v[104:105], v[98:99]
	v_lshl_add_u64 v[100:101], v[102:103], 1, s[78:79]
	v_add_f32_e32 v98, v98, v99
	v_fmamk_f32 v98, v98, 0x3a800000, v155
	v_rsq_f32_e32 v98, v98
	v_lshl_add_u64 v[100:101], v[100:101], 0, v[140:141]
	v_pk_mul_f32 v[96:97], v[96:97], v[98:99] op_sel_hi:[1,0]
	v_pk_mul_f32 v[94:95], v[94:95], v[98:99] op_sel_hi:[1,0]
	v_pk_mul_f32 v[102:103], v[92:93], v[98:99] op_sel_hi:[1,0]
	v_pk_mul_f32 v[92:93], v[90:91], v[98:99] op_sel_hi:[1,0]
	v_cvt_pk_bf16_f32 v90, v94, v95
	v_cvt_pk_bf16_f32 v91, v96, v97
	v_pk_mul_f32 v[88:89], v[88:89], v[98:99] op_sel_hi:[1,0]
	v_cvt_pk_bf16_f32 v92, v92, v93
	v_cvt_pk_bf16_f32 v93, v102, v103
	global_store_dwordx4 v[100:101], v[90:93], off
	v_pk_mul_f32 v[86:87], v[86:87], v[98:99] op_sel_hi:[1,0]
	s_nop 0
	v_pk_mul_f32 v[90:91], v[84:85], v[98:99] op_sel_hi:[1,0]
	v_pk_mul_f32 v[84:85], v[82:83], v[98:99] op_sel_hi:[1,0]
	v_cvt_pk_bf16_f32 v82, v86, v87
	v_cvt_pk_bf16_f32 v83, v88, v89
	v_or_b32_e32 v86, 48, v148
	v_cvt_pk_bf16_f32 v84, v84, v85
	v_cvt_pk_bf16_f32 v85, v90, v91
	global_store_dwordx4 v[100:101], v[82:85], off offset:256
	ds_read_b128 v[82:85], v147 offset:768
	v_mul_lo_u32 v90, s69, v86
	v_mad_u64_u32 v[86:87], s[16:17], s68, v86, 0
	v_add3_u32 v87, v87, v149, v90
	s_waitcnt lgkmcnt(0)
	v_mov_b32_e32 v88, v83
	v_mov_b32_e32 v89, v84
	v_mov_b32_e32 v83, v85
	v_pk_add_f32 v[82:83], v[88:89], v[82:83]
	v_lshl_add_u64 v[84:85], v[86:87], 1, s[78:79]
	v_add_f32_e32 v82, v82, v83
	v_fmamk_f32 v82, v82, 0x3a800000, v155
	v_rsq_f32_e32 v82, v82
	v_lshl_add_u64 v[84:85], v[84:85], 0, v[140:141]
	v_pk_mul_f32 v[80:81], v[80:81], v[82:83] op_sel_hi:[1,0]
	v_pk_mul_f32 v[78:79], v[78:79], v[82:83] op_sel_hi:[1,0]
	v_pk_mul_f32 v[86:87], v[76:77], v[82:83] op_sel_hi:[1,0]
	v_pk_mul_f32 v[76:77], v[74:75], v[82:83] op_sel_hi:[1,0]
	v_cvt_pk_bf16_f32 v74, v78, v79
	v_cvt_pk_bf16_f32 v75, v80, v81
	v_pk_mul_f32 v[72:73], v[72:73], v[82:83] op_sel_hi:[1,0]
	v_cvt_pk_bf16_f32 v76, v76, v77
	v_cvt_pk_bf16_f32 v77, v86, v87
	global_store_dwordx4 v[84:85], v[74:77], off
	v_pk_mul_f32 v[70:71], v[70:71], v[82:83] op_sel_hi:[1,0]
	s_nop 0
	v_pk_mul_f32 v[74:75], v[68:69], v[82:83] op_sel_hi:[1,0]
	v_pk_mul_f32 v[68:69], v[66:67], v[82:83] op_sel_hi:[1,0]
	v_cvt_pk_bf16_f32 v66, v70, v71
	v_cvt_pk_bf16_f32 v67, v72, v73
	v_add_u32_e32 v70, 0x80, v148
	v_cvt_pk_bf16_f32 v68, v68, v69
	v_cvt_pk_bf16_f32 v69, v74, v75
	global_store_dwordx4 v[84:85], v[66:69], off offset:256
	ds_read_b128 v[66:69], v147 offset:1024
	v_ashrrev_i32_e32 v71, 31, v70
	v_mul_lo_u32 v74, s68, v71
	v_mul_lo_u32 v75, s69, v70
	v_mad_u64_u32 v[70:71], s[16:17], s68, v70, 0
	s_waitcnt lgkmcnt(0)
	v_mov_b32_e32 v72, v67
	v_mov_b32_e32 v73, v68
	v_mov_b32_e32 v67, v69
	v_pk_add_f32 v[66:67], v[72:73], v[66:67]
	v_add3_u32 v71, v71, v74, v75
	v_add_f32_e32 v66, v66, v67
	v_fmamk_f32 v66, v66, 0x3a800000, v155
	v_rsq_f32_e32 v66, v66
	v_lshl_add_u64 v[68:69], v[70:71], 1, s[78:79]
	v_lshl_add_u64 v[68:69], v[68:69], 0, v[140:141]
	v_pk_mul_f32 v[64:65], v[64:65], v[66:67] op_sel_hi:[1,0]
	v_pk_mul_f32 v[62:63], v[62:63], v[66:67] op_sel_hi:[1,0]
	v_pk_mul_f32 v[70:71], v[60:61], v[66:67] op_sel_hi:[1,0]
	v_pk_mul_f32 v[60:61], v[58:59], v[66:67] op_sel_hi:[1,0]
	v_cvt_pk_bf16_f32 v58, v62, v63
	v_cvt_pk_bf16_f32 v59, v64, v65
	v_pk_mul_f32 v[56:57], v[56:57], v[66:67] op_sel_hi:[1,0]
	v_cvt_pk_bf16_f32 v60, v60, v61
	v_cvt_pk_bf16_f32 v61, v70, v71
	global_store_dwordx4 v[68:69], v[58:61], off
	v_pk_mul_f32 v[54:55], v[54:55], v[66:67] op_sel_hi:[1,0]
	s_nop 0
	v_pk_mul_f32 v[58:59], v[52:53], v[66:67] op_sel_hi:[1,0]
	v_pk_mul_f32 v[52:53], v[50:51], v[66:67] op_sel_hi:[1,0]
	v_cvt_pk_bf16_f32 v50, v54, v55
	v_cvt_pk_bf16_f32 v51, v56, v57
	v_add_u32_e32 v54, 0x90, v148
	v_cvt_pk_bf16_f32 v52, v52, v53
	v_cvt_pk_bf16_f32 v53, v58, v59
	global_store_dwordx4 v[68:69], v[50:53], off offset:256
	ds_read_b128 v[50:53], v147 offset:1280
	v_ashrrev_i32_e32 v55, 31, v54
	v_mul_lo_u32 v58, s68, v55
	v_mul_lo_u32 v59, s69, v54
	v_mad_u64_u32 v[54:55], s[16:17], s68, v54, 0
	s_waitcnt lgkmcnt(0)
	v_mov_b32_e32 v56, v51
	v_mov_b32_e32 v57, v52
	v_mov_b32_e32 v51, v53
	v_pk_add_f32 v[50:51], v[56:57], v[50:51]
	v_add3_u32 v55, v55, v58, v59
	v_add_f32_e32 v50, v50, v51
	v_fmamk_f32 v50, v50, 0x3a800000, v155
	v_rsq_f32_e32 v50, v50
	v_lshl_add_u64 v[52:53], v[54:55], 1, s[78:79]
	v_lshl_add_u64 v[52:53], v[52:53], 0, v[140:141]
	v_pk_mul_f32 v[48:49], v[48:49], v[50:51] op_sel_hi:[1,0]
	v_pk_mul_f32 v[46:47], v[46:47], v[50:51] op_sel_hi:[1,0]
	v_pk_mul_f32 v[54:55], v[44:45], v[50:51] op_sel_hi:[1,0]
	v_pk_mul_f32 v[44:45], v[42:43], v[50:51] op_sel_hi:[1,0]
	v_cvt_pk_bf16_f32 v42, v46, v47
	v_cvt_pk_bf16_f32 v43, v48, v49
	v_pk_mul_f32 v[40:41], v[40:41], v[50:51] op_sel_hi:[1,0]
	v_cvt_pk_bf16_f32 v44, v44, v45
	v_cvt_pk_bf16_f32 v45, v54, v55
	global_store_dwordx4 v[52:53], v[42:45], off
	v_pk_mul_f32 v[38:39], v[38:39], v[50:51] op_sel_hi:[1,0]
	s_nop 0
	v_pk_mul_f32 v[42:43], v[36:37], v[50:51] op_sel_hi:[1,0]
	v_pk_mul_f32 v[36:37], v[34:35], v[50:51] op_sel_hi:[1,0]
	v_cvt_pk_bf16_f32 v34, v38, v39
	v_cvt_pk_bf16_f32 v35, v40, v41
	v_add_u32_e32 v38, 0xa0, v148
	v_cvt_pk_bf16_f32 v36, v36, v37
	v_cvt_pk_bf16_f32 v37, v42, v43
	global_store_dwordx4 v[52:53], v[34:37], off offset:256
	ds_read_b128 v[34:37], v147 offset:1536
	v_ashrrev_i32_e32 v39, 31, v38
	v_mul_lo_u32 v42, s68, v39
	v_mul_lo_u32 v43, s69, v38
	v_mad_u64_u32 v[38:39], s[16:17], s68, v38, 0
	s_waitcnt lgkmcnt(0)
	v_mov_b32_e32 v40, v35
	v_mov_b32_e32 v41, v36
	v_mov_b32_e32 v35, v37
	v_pk_add_f32 v[34:35], v[40:41], v[34:35]
	v_add3_u32 v39, v39, v42, v43
	v_add_f32_e32 v34, v34, v35
	v_fmamk_f32 v34, v34, 0x3a800000, v155
	v_rsq_f32_e32 v34, v34
	v_lshl_add_u64 v[36:37], v[38:39], 1, s[78:79]
	v_lshl_add_u64 v[36:37], v[36:37], 0, v[140:141]
	v_pk_mul_f32 v[32:33], v[32:33], v[34:35] op_sel_hi:[1,0]
	v_pk_mul_f32 v[30:31], v[30:31], v[34:35] op_sel_hi:[1,0]
	v_pk_mul_f32 v[38:39], v[28:29], v[34:35] op_sel_hi:[1,0]
	v_pk_mul_f32 v[28:29], v[26:27], v[34:35] op_sel_hi:[1,0]
	v_cvt_pk_bf16_f32 v26, v30, v31
	v_cvt_pk_bf16_f32 v27, v32, v33
	v_pk_mul_f32 v[24:25], v[24:25], v[34:35] op_sel_hi:[1,0]
	v_cvt_pk_bf16_f32 v28, v28, v29
	v_cvt_pk_bf16_f32 v29, v38, v39
	global_store_dwordx4 v[36:37], v[26:29], off
	v_pk_mul_f32 v[22:23], v[22:23], v[34:35] op_sel_hi:[1,0]
	s_nop 0
	v_pk_mul_f32 v[26:27], v[20:21], v[34:35] op_sel_hi:[1,0]
	v_pk_mul_f32 v[20:21], v[18:19], v[34:35] op_sel_hi:[1,0]
	v_cvt_pk_bf16_f32 v18, v22, v23
	v_cvt_pk_bf16_f32 v19, v24, v25
	v_add_u32_e32 v22, 0xb0, v148
	v_cvt_pk_bf16_f32 v20, v20, v21
	v_cvt_pk_bf16_f32 v21, v26, v27
	global_store_dwordx4 v[36:37], v[18:21], off offset:256
	ds_read_b128 v[18:21], v147 offset:1792
	v_ashrrev_i32_e32 v23, 31, v22
	v_mul_lo_u32 v26, s68, v23
	v_mul_lo_u32 v27, s69, v22
	v_mad_u64_u32 v[22:23], s[16:17], s68, v22, 0
	s_waitcnt lgkmcnt(0)
	v_mov_b32_e32 v24, v19
	v_mov_b32_e32 v25, v20
	v_mov_b32_e32 v19, v21
	v_pk_add_f32 v[18:19], v[24:25], v[18:19]
	v_add3_u32 v23, v23, v26, v27
	v_add_f32_e32 v18, v18, v19
	v_fmamk_f32 v18, v18, 0x3a800000, v155
	v_rsq_f32_e32 v18, v18
	v_lshl_add_u64 v[20:21], v[22:23], 1, s[78:79]
	v_lshl_add_u64 v[20:21], v[20:21], 0, v[140:141]
	v_pk_mul_f32 v[16:17], v[16:17], v[18:19] op_sel_hi:[1,0]
	v_pk_mul_f32 v[14:15], v[14:15], v[18:19] op_sel_hi:[1,0]
	v_pk_mul_f32 v[22:23], v[12:13], v[18:19] op_sel_hi:[1,0]
	v_pk_mul_f32 v[12:13], v[10:11], v[18:19] op_sel_hi:[1,0]
	v_cvt_pk_bf16_f32 v10, v14, v15
	v_cvt_pk_bf16_f32 v11, v16, v17
	v_pk_mul_f32 v[8:9], v[8:9], v[18:19] op_sel_hi:[1,0]
	v_cvt_pk_bf16_f32 v12, v12, v13
	v_cvt_pk_bf16_f32 v13, v22, v23
	global_store_dwordx4 v[20:21], v[10:13], off
	v_pk_mul_f32 v[6:7], v[6:7], v[18:19] op_sel_hi:[1,0]
	s_nop 0
	v_pk_mul_f32 v[10:11], v[4:5], v[18:19] op_sel_hi:[1,0]
	v_pk_mul_f32 v[4:5], v[2:3], v[18:19] op_sel_hi:[1,0]
	v_cvt_pk_bf16_f32 v2, v6, v7
	v_cvt_pk_bf16_f32 v3, v8, v9
	s_nop 0
	v_cvt_pk_bf16_f32 v4, v4, v5
	v_cvt_pk_bf16_f32 v5, v10, v11
	global_store_dwordx4 v[20:21], v[2:5], off offset:256
	s_cbranch_vccnz .LBB0_410
	s_mov_b32 s101, 1
	s_nop 0
	v_lshl_add_u32 v2, s61, 8, v145
	v_ashrrev_i32_e32 v3, 31, v2
	s_mov_b32 m0, s31
	v_lshl_add_u64 v[2:3], v[2:3], 4, s[96:97]
	global_load_lds_dwordx4 v[2:3], off
	v_lshl_add_u64 v[2:3], v[2:3], 0, s[82:83]
	s_add_i32 m0, s31, 0x400
	s_andn2_b64 vcc, exec, s[8:9]
	global_load_lds_dwordx4 v[2:3], off
	s_cbranch_vccnz .LBB0_409
	s_barrier
	s_branch .LBB0_409
